# v5 + write-through (sc1) GEMM epilogue stores so the grid barrier's L2 write-back has less to flush
# baseline (speedup 1.0000x reference)
.LBB0_132:
	s_lshl_b32 s10, s42, 8
	s_cmp_lt_i32 s42, 16
	s_cselect_b32 s11, 0, 0x1000
	s_lshl_b32 s1, s40, 8
	s_and_b32 s31, s1, 0xf00
	s_ashr_i32 s1, s0, 31
	s_lshl_b64 s[0:1], s[0:1], 26
	s_add_u32 s0, s58, s0
	v_cvt_pk_bf16_f32 v126, v126, v127
	v_cvt_pk_bf16_f32 v127, v128, v129
	v_cvt_pk_bf16_f32 v128, v122, v123
	s_addc_u32 s1, s59, s1
	v_lshrrev_b32_e32 v122, 2, v126
	s_add_i32 s11, s11, s10
	v_and_b32_e32 v122, 0x10001, v122
	v_or_b32_e32 v138, s31, v155
	v_add_u32_e32 v148, s11, v1
	v_cvt_pk_bf16_f32 v125, v124, v125
	v_add3_u32 v122, v126, v122, s66
	v_lshrrev_b32_e32 v123, 2, v127
	v_lshrrev_b32_e32 v124, 2, v128
	v_lshrrev_b32_e32 v126, 2, v125
	v_lshlrev_b32_e32 v138, 1, v138
	v_ashrrev_i32_e32 v149, 31, v148
	v_and_b32_e32 v123, 0x10001, v123
	v_and_b32_e32 v124, 0x10001, v124
	v_and_b32_e32 v126, 0x10001, v126
	v_lshl_add_u64 v[150:151], s[0:1], 0, v[138:139]
	v_lshlrev_b64 v[152:153], 13, v[148:149]
	v_add3_u32 v123, v127, v123, s66
	v_add3_u32 v124, v128, v124, s66
	v_add3_u32 v125, v125, v126, s66
	v_cndmask_b32_e64 v126, 0, 1, s[44:45]
	v_lshl_add_u64 v[152:153], v[150:151], 0, v[152:153]
	v_and_b32_e32 v122, 0xfffcfffc, v122
	v_and_b32_e32 v123, 0xfffcfffc, v123
	v_and_b32_e32 v124, 0xfffcfffc, v124
	v_and_b32_e32 v125, 0xfffcfffc, v125
	v_cmp_ne_u32_e64 s[10:11], 1, v126
	s_andn2_b64 vcc, exec, s[44:45]
	global_store_dwordx4 v[152:153], v[122:125], off sc1
	s_cbranch_vccnz .LBB0_134
	s_nop 0
	v_mul_f32_e32 v123, 0xbfb8aa3b, v114
	v_mul_f32_e32 v124, 0xbfb8aa3b, v119
	v_exp_f32_e32 v123, v123
	v_exp_f32_e32 v125, v124
	v_mul_f32_e32 v127, 0xbfb8aa3b, v116
	v_mul_f32_e32 v128, 0xbfb8aa3b, v121
	v_add_f32_e32 v123, 1.0, v123
	v_mul_f32_e32 v122, 0xbfb8aa3b, v118
	v_rcp_f32_e32 v124, v123
	v_add_f32_e32 v123, 1.0, v125
	v_mul_f32_e32 v125, 0xbfb8aa3b, v115
	v_mul_f32_e32 v126, 0xbfb8aa3b, v120
	v_exp_f32_e32 v127, v127
	v_exp_f32_e32 v129, v128
	v_mul_f32_e32 v128, 0xbfb8aa3b, v117
	v_exp_f32_e32 v122, v122
	v_exp_f32_e32 v125, v125
	v_exp_f32_e32 v126, v126
	v_exp_f32_e32 v138, v128
	v_add_f32_e32 v127, 1.0, v127
	v_add_f32_e32 v122, 1.0, v122
	v_add_f32_e32 v125, 1.0, v125
	v_add_f32_e32 v126, 1.0, v126
	v_rcp_f32_e32 v128, v127
	v_add_f32_e32 v127, 1.0, v129
	v_add_f32_e32 v129, 1.0, v138
	v_rcp_f32_e32 v122, v122
	v_rcp_f32_e32 v123, v123
	v_rcp_f32_e32 v126, v126
	v_rcp_f32_e32 v127, v127
	v_rcp_f32_e32 v129, v129
	v_rcp_f32_e32 v125, v125
	v_pk_mul_f32 v[118:119], v[118:119], v[122:123]
	v_pk_mul_f32 v[120:121], v[120:121], v[126:127]
	v_pk_mul_f32 v[116:117], v[116:117], v[128:129]
	v_pk_mul_f32 v[114:115], v[114:115], v[124:125]
.LBB0_134:
	v_cvt_pk_bf16_f32 v118, v118, v119
	v_cvt_pk_bf16_f32 v119, v120, v121
	s_nop 0
	v_cvt_pk_bf16_f32 v120, v114, v115
	v_cvt_pk_bf16_f32 v117, v116, v117
	s_and_b64 vcc, exec, s[10:11]
	v_lshrrev_b32_e32 v114, 2, v118
	v_and_b32_e32 v114, 0x10001, v114
	v_add3_u32 v114, v118, v114, s66
	v_lshrrev_b32_e32 v115, 2, v119
	v_lshrrev_b32_e32 v116, 2, v120
	v_lshrrev_b32_e32 v118, 2, v117
	v_and_b32_e32 v115, 0x10001, v115
	v_and_b32_e32 v116, 0x10001, v116
	v_and_b32_e32 v118, 0x10001, v118
	v_add3_u32 v115, v119, v115, s66
	v_add3_u32 v116, v120, v116, s66
	v_add3_u32 v117, v117, v118, s66
	v_and_b32_e32 v114, 0xfffcfffc, v114
	v_and_b32_e32 v115, 0xfffcfffc, v115
	v_and_b32_e32 v116, 0xfffcfffc, v116
	v_and_b32_e32 v117, 0xfffcfffc, v117
	global_store_dwordx4 v[152:153], v[114:117], off offset:256 sc1
	s_cbranch_vccnz .LBB0_136
	s_nop 0
	v_mul_f32_e32 v115, 0xbfb8aa3b, v106
	v_mul_f32_e32 v116, 0xbfb8aa3b, v111
	v_exp_f32_e32 v115, v115
	v_exp_f32_e32 v117, v116
	v_mul_f32_e32 v119, 0xbfb8aa3b, v108
	v_mul_f32_e32 v120, 0xbfb8aa3b, v113
	v_add_f32_e32 v115, 1.0, v115
	v_mul_f32_e32 v114, 0xbfb8aa3b, v110
	v_rcp_f32_e32 v116, v115
	v_add_f32_e32 v115, 1.0, v117
	v_mul_f32_e32 v117, 0xbfb8aa3b, v107
	v_mul_f32_e32 v118, 0xbfb8aa3b, v112
	v_exp_f32_e32 v119, v119
	v_exp_f32_e32 v121, v120
	v_mul_f32_e32 v120, 0xbfb8aa3b, v109
	v_exp_f32_e32 v114, v114
	v_exp_f32_e32 v117, v117
	v_exp_f32_e32 v118, v118
	v_exp_f32_e32 v122, v120
	v_add_f32_e32 v119, 1.0, v119
	v_add_f32_e32 v114, 1.0, v114
	v_add_f32_e32 v117, 1.0, v117
	v_add_f32_e32 v118, 1.0, v118
	v_rcp_f32_e32 v120, v119
	v_add_f32_e32 v119, 1.0, v121
	v_add_f32_e32 v121, 1.0, v122
	v_rcp_f32_e32 v114, v114
	v_rcp_f32_e32 v115, v115
	v_rcp_f32_e32 v118, v118
	v_rcp_f32_e32 v119, v119
	v_rcp_f32_e32 v121, v121
	v_rcp_f32_e32 v117, v117
	v_pk_mul_f32 v[110:111], v[110:111], v[114:115]
	v_pk_mul_f32 v[112:113], v[112:113], v[118:119]
	v_pk_mul_f32 v[108:109], v[108:109], v[120:121]
	v_pk_mul_f32 v[106:107], v[106:107], v[116:117]
.LBB0_136:
	v_cvt_pk_bf16_f32 v110, v110, v111
	v_cvt_pk_bf16_f32 v111, v112, v113
	s_nop 0
	v_cvt_pk_bf16_f32 v112, v106, v107
	v_or_b32_e32 v114, 16, v148
	v_lshrrev_b32_e32 v106, 2, v110
	v_and_b32_e32 v106, 0x10001, v106
	v_cvt_pk_bf16_f32 v109, v108, v109
	v_add3_u32 v106, v110, v106, s66
	v_lshrrev_b32_e32 v107, 2, v111
	v_lshrrev_b32_e32 v108, 2, v112
	v_lshrrev_b32_e32 v110, 2, v109
	v_ashrrev_i32_e32 v115, 31, v114
	v_and_b32_e32 v107, 0x10001, v107
	v_and_b32_e32 v108, 0x10001, v108
	v_and_b32_e32 v110, 0x10001, v110
	v_lshlrev_b64 v[114:115], 13, v[114:115]
	v_add3_u32 v107, v111, v107, s66
	v_add3_u32 v108, v112, v108, s66
	v_add3_u32 v109, v109, v110, s66
	v_lshl_add_u64 v[114:115], v[150:151], 0, v[114:115]
	v_and_b32_e32 v106, 0xfffcfffc, v106
	v_and_b32_e32 v107, 0xfffcfffc, v107
	v_and_b32_e32 v108, 0xfffcfffc, v108
	v_and_b32_e32 v109, 0xfffcfffc, v109
	s_and_b64 vcc, exec, s[10:11]
	global_store_dwordx4 v[114:115], v[106:109], off sc1
	s_cbranch_vccnz .LBB0_138
	s_nop 0
	v_mul_f32_e32 v107, 0xbfb8aa3b, v98
	v_mul_f32_e32 v108, 0xbfb8aa3b, v103
	v_exp_f32_e32 v107, v107
	v_exp_f32_e32 v109, v108
	v_mul_f32_e32 v111, 0xbfb8aa3b, v100
	v_mul_f32_e32 v112, 0xbfb8aa3b, v105
	v_add_f32_e32 v107, 1.0, v107
	v_mul_f32_e32 v106, 0xbfb8aa3b, v102
	v_rcp_f32_e32 v108, v107
	v_add_f32_e32 v107, 1.0, v109
	v_mul_f32_e32 v109, 0xbfb8aa3b, v99
	v_mul_f32_e32 v110, 0xbfb8aa3b, v104
	v_exp_f32_e32 v111, v111
	v_exp_f32_e32 v113, v112
	v_mul_f32_e32 v112, 0xbfb8aa3b, v101
	v_exp_f32_e32 v106, v106
	v_exp_f32_e32 v109, v109
	v_exp_f32_e32 v110, v110
	v_exp_f32_e32 v116, v112
	v_add_f32_e32 v111, 1.0, v111
	v_add_f32_e32 v106, 1.0, v106
	v_add_f32_e32 v109, 1.0, v109
	v_add_f32_e32 v110, 1.0, v110
	v_rcp_f32_e32 v112, v111
	v_add_f32_e32 v111, 1.0, v113
	v_add_f32_e32 v113, 1.0, v116
	v_rcp_f32_e32 v106, v106
	v_rcp_f32_e32 v107, v107
	v_rcp_f32_e32 v110, v110
	v_rcp_f32_e32 v111, v111
	v_rcp_f32_e32 v113, v113
	v_rcp_f32_e32 v109, v109
	v_pk_mul_f32 v[102:103], v[102:103], v[106:107]
	v_pk_mul_f32 v[104:105], v[104:105], v[110:111]
	v_pk_mul_f32 v[100:101], v[100:101], v[112:113]
	v_pk_mul_f32 v[98:99], v[98:99], v[108:109]
.LBB0_138:
	v_cvt_pk_bf16_f32 v102, v102, v103
	v_cvt_pk_bf16_f32 v103, v104, v105
	s_nop 0
	v_cvt_pk_bf16_f32 v104, v98, v99
	v_cvt_pk_bf16_f32 v101, v100, v101
	s_and_b64 vcc, exec, s[10:11]
	v_lshrrev_b32_e32 v98, 2, v102
	v_and_b32_e32 v98, 0x10001, v98
	v_add3_u32 v98, v102, v98, s66
	v_lshrrev_b32_e32 v99, 2, v103
	v_lshrrev_b32_e32 v100, 2, v104
	v_lshrrev_b32_e32 v102, 2, v101
	v_and_b32_e32 v99, 0x10001, v99
	v_and_b32_e32 v100, 0x10001, v100
	v_and_b32_e32 v102, 0x10001, v102
	v_add3_u32 v99, v103, v99, s66
	v_add3_u32 v100, v104, v100, s66
	v_add3_u32 v101, v101, v102, s66
	v_and_b32_e32 v98, 0xfffcfffc, v98
	v_and_b32_e32 v99, 0xfffcfffc, v99
	v_and_b32_e32 v100, 0xfffcfffc, v100
	v_and_b32_e32 v101, 0xfffcfffc, v101
	global_store_dwordx4 v[114:115], v[98:101], off offset:256 sc1
	s_cbranch_vccnz .LBB0_140
	s_nop 0
	v_mul_f32_e32 v99, 0xbfb8aa3b, v90
	v_mul_f32_e32 v100, 0xbfb8aa3b, v95
	v_exp_f32_e32 v99, v99
	v_exp_f32_e32 v101, v100
	v_mul_f32_e32 v103, 0xbfb8aa3b, v92
	v_mul_f32_e32 v104, 0xbfb8aa3b, v97
	v_add_f32_e32 v99, 1.0, v99
	v_mul_f32_e32 v98, 0xbfb8aa3b, v94
	v_rcp_f32_e32 v100, v99
	v_add_f32_e32 v99, 1.0, v101
	v_mul_f32_e32 v101, 0xbfb8aa3b, v91
	v_mul_f32_e32 v102, 0xbfb8aa3b, v96
	v_exp_f32_e32 v103, v103
	v_exp_f32_e32 v105, v104
	v_mul_f32_e32 v104, 0xbfb8aa3b, v93
	v_exp_f32_e32 v98, v98
	v_exp_f32_e32 v101, v101
	v_exp_f32_e32 v102, v102
	v_exp_f32_e32 v106, v104
	v_add_f32_e32 v103, 1.0, v103
	v_add_f32_e32 v98, 1.0, v98
	v_add_f32_e32 v101, 1.0, v101
	v_add_f32_e32 v102, 1.0, v102
	v_rcp_f32_e32 v104, v103
	v_add_f32_e32 v103, 1.0, v105
	v_add_f32_e32 v105, 1.0, v106
	v_rcp_f32_e32 v98, v98
	v_rcp_f32_e32 v99, v99
	v_rcp_f32_e32 v102, v102
	v_rcp_f32_e32 v103, v103
	v_rcp_f32_e32 v105, v105
	v_rcp_f32_e32 v101, v101
	v_pk_mul_f32 v[94:95], v[94:95], v[98:99]
	v_pk_mul_f32 v[96:97], v[96:97], v[102:103]
	v_pk_mul_f32 v[92:93], v[92:93], v[104:105]
	v_pk_mul_f32 v[90:91], v[90:91], v[100:101]
.LBB0_140:
	v_cvt_pk_bf16_f32 v94, v94, v95
	v_cvt_pk_bf16_f32 v95, v96, v97
	s_nop 0
	v_cvt_pk_bf16_f32 v96, v90, v91
	v_or_b32_e32 v98, 32, v148
	v_lshrrev_b32_e32 v90, 2, v94
	v_and_b32_e32 v90, 0x10001, v90
	v_cvt_pk_bf16_f32 v93, v92, v93
	v_add3_u32 v90, v94, v90, s66
	v_lshrrev_b32_e32 v91, 2, v95
	v_lshrrev_b32_e32 v92, 2, v96
	v_lshrrev_b32_e32 v94, 2, v93
	v_ashrrev_i32_e32 v99, 31, v98
	v_and_b32_e32 v91, 0x10001, v91
	v_and_b32_e32 v92, 0x10001, v92
	v_and_b32_e32 v94, 0x10001, v94
	v_lshlrev_b64 v[98:99], 13, v[98:99]
	v_add3_u32 v91, v95, v91, s66
	v_add3_u32 v92, v96, v92, s66
	v_add3_u32 v93, v93, v94, s66
	v_lshl_add_u64 v[98:99], v[150:151], 0, v[98:99]
	v_and_b32_e32 v90, 0xfffcfffc, v90
	v_and_b32_e32 v91, 0xfffcfffc, v91
	v_and_b32_e32 v92, 0xfffcfffc, v92
	v_and_b32_e32 v93, 0xfffcfffc, v93
	s_and_b64 vcc, exec, s[10:11]
	global_store_dwordx4 v[98:99], v[90:93], off sc1
	s_cbranch_vccnz .LBB0_142
	s_nop 0
	v_mul_f32_e32 v91, 0xbfb8aa3b, v82
	v_mul_f32_e32 v92, 0xbfb8aa3b, v87
	v_exp_f32_e32 v91, v91
	v_exp_f32_e32 v93, v92
	v_mul_f32_e32 v95, 0xbfb8aa3b, v84
	v_mul_f32_e32 v96, 0xbfb8aa3b, v89
	v_add_f32_e32 v91, 1.0, v91
	v_mul_f32_e32 v90, 0xbfb8aa3b, v86
	v_rcp_f32_e32 v92, v91
	v_add_f32_e32 v91, 1.0, v93
	v_mul_f32_e32 v93, 0xbfb8aa3b, v83
	v_mul_f32_e32 v94, 0xbfb8aa3b, v88
	v_exp_f32_e32 v95, v95
	v_exp_f32_e32 v97, v96
	v_mul_f32_e32 v96, 0xbfb8aa3b, v85
	v_exp_f32_e32 v90, v90
	v_exp_f32_e32 v93, v93
	v_exp_f32_e32 v94, v94
	v_exp_f32_e32 v100, v96
	v_add_f32_e32 v95, 1.0, v95
	v_add_f32_e32 v90, 1.0, v90
	v_add_f32_e32 v93, 1.0, v93
	v_add_f32_e32 v94, 1.0, v94
	v_rcp_f32_e32 v96, v95
	v_add_f32_e32 v95, 1.0, v97
	v_add_f32_e32 v97, 1.0, v100
	v_rcp_f32_e32 v90, v90
	v_rcp_f32_e32 v91, v91
	v_rcp_f32_e32 v94, v94
	v_rcp_f32_e32 v95, v95
	v_rcp_f32_e32 v97, v97
	v_rcp_f32_e32 v93, v93
	v_pk_mul_f32 v[86:87], v[86:87], v[90:91]
	v_pk_mul_f32 v[88:89], v[88:89], v[94:95]
	v_pk_mul_f32 v[84:85], v[84:85], v[96:97]
	v_pk_mul_f32 v[82:83], v[82:83], v[92:93]
.LBB0_142:
	v_cvt_pk_bf16_f32 v86, v86, v87
	v_cvt_pk_bf16_f32 v87, v88, v89
	s_nop 0
	v_cvt_pk_bf16_f32 v88, v82, v83
	v_cvt_pk_bf16_f32 v85, v84, v85
	s_and_b64 vcc, exec, s[10:11]
	v_lshrrev_b32_e32 v82, 2, v86
	v_and_b32_e32 v82, 0x10001, v82
	v_add3_u32 v82, v86, v82, s66
	v_lshrrev_b32_e32 v83, 2, v87
	v_lshrrev_b32_e32 v84, 2, v88
	v_lshrrev_b32_e32 v86, 2, v85
	v_and_b32_e32 v83, 0x10001, v83
	v_and_b32_e32 v84, 0x10001, v84
	v_and_b32_e32 v86, 0x10001, v86
	v_add3_u32 v83, v87, v83, s66
	v_add3_u32 v84, v88, v84, s66
	v_add3_u32 v85, v85, v86, s66
	v_and_b32_e32 v82, 0xfffcfffc, v82
	v_and_b32_e32 v83, 0xfffcfffc, v83
	v_and_b32_e32 v84, 0xfffcfffc, v84
	v_and_b32_e32 v85, 0xfffcfffc, v85
	global_store_dwordx4 v[98:99], v[82:85], off offset:256 sc1
	s_cbranch_vccnz .LBB0_144
	s_nop 0
	v_mul_f32_e32 v83, 0xbfb8aa3b, v74
	v_mul_f32_e32 v84, 0xbfb8aa3b, v79
	v_exp_f32_e32 v83, v83
	v_exp_f32_e32 v85, v84
	v_mul_f32_e32 v87, 0xbfb8aa3b, v76
	v_mul_f32_e32 v88, 0xbfb8aa3b, v81
	v_add_f32_e32 v83, 1.0, v83
	v_mul_f32_e32 v82, 0xbfb8aa3b, v78
	v_rcp_f32_e32 v84, v83
	v_add_f32_e32 v83, 1.0, v85
	v_mul_f32_e32 v85, 0xbfb8aa3b, v75
	v_mul_f32_e32 v86, 0xbfb8aa3b, v80
	v_exp_f32_e32 v87, v87
	v_exp_f32_e32 v89, v88
	v_mul_f32_e32 v88, 0xbfb8aa3b, v77
	v_exp_f32_e32 v82, v82
	v_exp_f32_e32 v85, v85
	v_exp_f32_e32 v86, v86
	v_exp_f32_e32 v90, v88
	v_add_f32_e32 v87, 1.0, v87
	v_add_f32_e32 v82, 1.0, v82
	v_add_f32_e32 v85, 1.0, v85
	v_add_f32_e32 v86, 1.0, v86
	v_rcp_f32_e32 v88, v87
	v_add_f32_e32 v87, 1.0, v89
	v_add_f32_e32 v89, 1.0, v90
	v_rcp_f32_e32 v82, v82
	v_rcp_f32_e32 v83, v83
	v_rcp_f32_e32 v86, v86
	v_rcp_f32_e32 v87, v87
	v_rcp_f32_e32 v89, v89
	v_rcp_f32_e32 v85, v85
	v_pk_mul_f32 v[78:79], v[78:79], v[82:83]
	v_pk_mul_f32 v[80:81], v[80:81], v[86:87]
	v_pk_mul_f32 v[76:77], v[76:77], v[88:89]
	v_pk_mul_f32 v[74:75], v[74:75], v[84:85]
.LBB0_144:
	v_cvt_pk_bf16_f32 v78, v78, v79
	v_cvt_pk_bf16_f32 v79, v80, v81
	s_nop 0
	v_cvt_pk_bf16_f32 v80, v74, v75
	v_or_b32_e32 v82, 48, v148
	v_lshrrev_b32_e32 v74, 2, v78
	v_and_b32_e32 v74, 0x10001, v74
	v_cvt_pk_bf16_f32 v77, v76, v77
	v_add3_u32 v74, v78, v74, s66
	v_lshrrev_b32_e32 v75, 2, v79
	v_lshrrev_b32_e32 v76, 2, v80
	v_lshrrev_b32_e32 v78, 2, v77
	v_ashrrev_i32_e32 v83, 31, v82
	v_and_b32_e32 v75, 0x10001, v75
	v_and_b32_e32 v76, 0x10001, v76
	v_and_b32_e32 v78, 0x10001, v78
	v_lshlrev_b64 v[82:83], 13, v[82:83]
	v_add3_u32 v75, v79, v75, s66
	v_add3_u32 v76, v80, v76, s66
	v_add3_u32 v77, v77, v78, s66
	v_lshl_add_u64 v[82:83], v[150:151], 0, v[82:83]
	v_and_b32_e32 v74, 0xfffcfffc, v74
	v_and_b32_e32 v75, 0xfffcfffc, v75
	v_and_b32_e32 v76, 0xfffcfffc, v76
	v_and_b32_e32 v77, 0xfffcfffc, v77
	s_and_b64 vcc, exec, s[10:11]
	global_store_dwordx4 v[82:83], v[74:77], off sc1
	s_cbranch_vccnz .LBB0_146
	s_nop 0
	v_mul_f32_e32 v75, 0xbfb8aa3b, v66
	v_mul_f32_e32 v76, 0xbfb8aa3b, v71
	v_exp_f32_e32 v75, v75
	v_exp_f32_e32 v77, v76
	v_mul_f32_e32 v79, 0xbfb8aa3b, v68
	v_mul_f32_e32 v80, 0xbfb8aa3b, v73
	v_add_f32_e32 v75, 1.0, v75
	v_mul_f32_e32 v74, 0xbfb8aa3b, v70
	v_rcp_f32_e32 v76, v75
	v_add_f32_e32 v75, 1.0, v77
	v_mul_f32_e32 v77, 0xbfb8aa3b, v67
	v_mul_f32_e32 v78, 0xbfb8aa3b, v72
	v_exp_f32_e32 v79, v79
	v_exp_f32_e32 v81, v80
	v_mul_f32_e32 v80, 0xbfb8aa3b, v69
	v_exp_f32_e32 v74, v74
	v_exp_f32_e32 v77, v77
	v_exp_f32_e32 v78, v78
	v_exp_f32_e32 v84, v80
	v_add_f32_e32 v79, 1.0, v79
	v_add_f32_e32 v74, 1.0, v74
	v_add_f32_e32 v77, 1.0, v77
	v_add_f32_e32 v78, 1.0, v78
	v_rcp_f32_e32 v80, v79
	v_add_f32_e32 v79, 1.0, v81
	v_add_f32_e32 v81, 1.0, v84
	v_rcp_f32_e32 v74, v74
	v_rcp_f32_e32 v75, v75
	v_rcp_f32_e32 v78, v78
	v_rcp_f32_e32 v79, v79
	v_rcp_f32_e32 v81, v81
	v_rcp_f32_e32 v77, v77
	v_pk_mul_f32 v[70:71], v[70:71], v[74:75]
	v_pk_mul_f32 v[72:73], v[72:73], v[78:79]
	v_pk_mul_f32 v[68:69], v[68:69], v[80:81]
	v_pk_mul_f32 v[66:67], v[66:67], v[76:77]
.LBB0_146:
	v_cvt_pk_bf16_f32 v70, v70, v71
	v_cvt_pk_bf16_f32 v71, v72, v73
	s_nop 0
	v_cvt_pk_bf16_f32 v72, v66, v67
	v_cvt_pk_bf16_f32 v69, v68, v69
	s_and_b64 vcc, exec, s[10:11]
	v_lshrrev_b32_e32 v66, 2, v70
	v_and_b32_e32 v66, 0x10001, v66
	v_add3_u32 v66, v70, v66, s66
	v_lshrrev_b32_e32 v67, 2, v71
	v_lshrrev_b32_e32 v68, 2, v72
	v_lshrrev_b32_e32 v70, 2, v69
	v_and_b32_e32 v67, 0x10001, v67
	v_and_b32_e32 v68, 0x10001, v68
	v_and_b32_e32 v70, 0x10001, v70
	v_add3_u32 v67, v71, v67, s66
	v_add3_u32 v68, v72, v68, s66
	v_add3_u32 v69, v69, v70, s66
	v_and_b32_e32 v66, 0xfffcfffc, v66
	v_and_b32_e32 v67, 0xfffcfffc, v67
	v_and_b32_e32 v68, 0xfffcfffc, v68
	v_and_b32_e32 v69, 0xfffcfffc, v69
	global_store_dwordx4 v[82:83], v[66:69], off offset:256 sc1
	s_cbranch_vccnz .LBB0_148
	s_nop 0
	v_mul_f32_e32 v67, 0xbfb8aa3b, v58
	v_mul_f32_e32 v68, 0xbfb8aa3b, v63
	v_exp_f32_e32 v67, v67
	v_exp_f32_e32 v69, v68
	v_mul_f32_e32 v71, 0xbfb8aa3b, v60
	v_mul_f32_e32 v72, 0xbfb8aa3b, v65
	v_add_f32_e32 v67, 1.0, v67
	v_mul_f32_e32 v66, 0xbfb8aa3b, v62
	v_rcp_f32_e32 v68, v67
	v_add_f32_e32 v67, 1.0, v69
	v_mul_f32_e32 v69, 0xbfb8aa3b, v59
	v_mul_f32_e32 v70, 0xbfb8aa3b, v64
	v_exp_f32_e32 v71, v71
	v_exp_f32_e32 v73, v72
	v_mul_f32_e32 v72, 0xbfb8aa3b, v61
	v_exp_f32_e32 v66, v66
	v_exp_f32_e32 v69, v69
	v_exp_f32_e32 v70, v70
	v_exp_f32_e32 v74, v72
	v_add_f32_e32 v71, 1.0, v71
	v_add_f32_e32 v66, 1.0, v66
	v_add_f32_e32 v69, 1.0, v69
	v_add_f32_e32 v70, 1.0, v70
	v_rcp_f32_e32 v72, v71
	v_add_f32_e32 v71, 1.0, v73
	v_add_f32_e32 v73, 1.0, v74
	v_rcp_f32_e32 v66, v66
	v_rcp_f32_e32 v67, v67
	v_rcp_f32_e32 v70, v70
	v_rcp_f32_e32 v71, v71
	v_rcp_f32_e32 v73, v73
	v_rcp_f32_e32 v69, v69
	v_pk_mul_f32 v[62:63], v[62:63], v[66:67]
	v_pk_mul_f32 v[64:65], v[64:65], v[70:71]
	v_pk_mul_f32 v[60:61], v[60:61], v[72:73]
	v_pk_mul_f32 v[58:59], v[58:59], v[68:69]
.LBB0_148:
	v_cvt_pk_bf16_f32 v62, v62, v63
	v_cvt_pk_bf16_f32 v63, v64, v65
	s_nop 0
	v_cvt_pk_bf16_f32 v64, v58, v59
	v_lshlrev_b64 v[66:67], 13, v[148:149]
	v_lshrrev_b32_e32 v58, 2, v62
	v_and_b32_e32 v58, 0x10001, v58
	v_cvt_pk_bf16_f32 v61, v60, v61
	v_add3_u32 v58, v62, v58, s66
	v_lshrrev_b32_e32 v62, 2, v61
	v_lshl_add_u64 v[66:67], v[150:151], 0, v[66:67]
	v_lshrrev_b32_e32 v59, 2, v63
	v_lshrrev_b32_e32 v60, 2, v64
	v_and_b32_e32 v62, 0x10001, v62
	v_and_b32_e32 v59, 0x10001, v59
	v_and_b32_e32 v60, 0x10001, v60
	v_add3_u32 v61, v61, v62, s66
	v_add_co_u32_e32 v62, vcc, 0x100000, v66
	v_add3_u32 v59, v63, v59, s66
	v_add3_u32 v60, v64, v60, s66
	v_addc_co_u32_e32 v63, vcc, 0, v67, vcc
	v_and_b32_e32 v58, 0xfffcfffc, v58
	v_and_b32_e32 v59, 0xfffcfffc, v59
	v_and_b32_e32 v60, 0xfffcfffc, v60
	v_and_b32_e32 v61, 0xfffcfffc, v61
	s_and_b64 vcc, exec, s[10:11]
	global_store_dwordx4 v[62:63], v[58:61], off sc1
	s_cbranch_vccnz .LBB0_150
	s_nop 0
	v_mul_f32_e32 v59, 0xbfb8aa3b, v50
	v_mul_f32_e32 v60, 0xbfb8aa3b, v55
	v_exp_f32_e32 v59, v59
	v_exp_f32_e32 v61, v60
	v_mul_f32_e32 v63, 0xbfb8aa3b, v52
	v_mul_f32_e32 v64, 0xbfb8aa3b, v57
	v_add_f32_e32 v59, 1.0, v59
	v_mul_f32_e32 v58, 0xbfb8aa3b, v54
	v_rcp_f32_e32 v60, v59
	v_add_f32_e32 v59, 1.0, v61
	v_mul_f32_e32 v61, 0xbfb8aa3b, v51
	v_mul_f32_e32 v62, 0xbfb8aa3b, v56
	v_exp_f32_e32 v63, v63
	v_exp_f32_e32 v65, v64
	v_mul_f32_e32 v64, 0xbfb8aa3b, v53
	v_exp_f32_e32 v58, v58
	v_exp_f32_e32 v61, v61
	v_exp_f32_e32 v62, v62
	v_exp_f32_e32 v68, v64
	v_add_f32_e32 v63, 1.0, v63
	v_add_f32_e32 v58, 1.0, v58
	v_add_f32_e32 v61, 1.0, v61
	v_add_f32_e32 v62, 1.0, v62
	v_rcp_f32_e32 v64, v63
	v_add_f32_e32 v63, 1.0, v65
	v_add_f32_e32 v65, 1.0, v68
	v_rcp_f32_e32 v58, v58
	v_rcp_f32_e32 v59, v59
	v_rcp_f32_e32 v62, v62
	v_rcp_f32_e32 v63, v63
	v_rcp_f32_e32 v65, v65
	v_rcp_f32_e32 v61, v61
	v_pk_mul_f32 v[54:55], v[54:55], v[58:59]
	v_pk_mul_f32 v[56:57], v[56:57], v[62:63]
	v_pk_mul_f32 v[52:53], v[52:53], v[64:65]
	v_pk_mul_f32 v[50:51], v[50:51], v[60:61]
.LBB0_150:
	v_cvt_pk_bf16_f32 v54, v54, v55
	v_cvt_pk_bf16_f32 v55, v56, v57
	s_nop 0
	v_cvt_pk_bf16_f32 v56, v50, v51
	v_cvt_pk_bf16_f32 v53, v52, v53
	v_lshl_add_u64 v[58:59], v[66:67], 0, s[18:19]
	v_lshrrev_b32_e32 v50, 2, v54
	v_and_b32_e32 v50, 0x10001, v50
	v_add3_u32 v50, v54, v50, s66
	v_lshrrev_b32_e32 v51, 2, v55
	v_lshrrev_b32_e32 v52, 2, v56
	v_lshrrev_b32_e32 v54, 2, v53
	v_and_b32_e32 v51, 0x10001, v51
	v_and_b32_e32 v52, 0x10001, v52
	v_and_b32_e32 v54, 0x10001, v54
	v_add3_u32 v51, v55, v51, s66
	v_add3_u32 v52, v56, v52, s66
	v_add3_u32 v53, v53, v54, s66
	v_and_b32_e32 v50, 0xfffcfffc, v50
	v_and_b32_e32 v51, 0xfffcfffc, v51
	v_and_b32_e32 v52, 0xfffcfffc, v52
	v_and_b32_e32 v53, 0xfffcfffc, v53
	s_and_b64 vcc, exec, s[10:11]
	global_store_dwordx4 v[58:59], v[50:53], off offset:256 sc1
	s_cbranch_vccnz .LBB0_152
	s_nop 0
	v_mul_f32_e32 v51, 0xbfb8aa3b, v42
	v_mul_f32_e32 v52, 0xbfb8aa3b, v47
	v_exp_f32_e32 v51, v51
	v_exp_f32_e32 v53, v52
	v_mul_f32_e32 v55, 0xbfb8aa3b, v44
	v_mul_f32_e32 v56, 0xbfb8aa3b, v49
	v_add_f32_e32 v51, 1.0, v51
	v_mul_f32_e32 v50, 0xbfb8aa3b, v46
	v_rcp_f32_e32 v52, v51
	v_add_f32_e32 v51, 1.0, v53
	v_mul_f32_e32 v53, 0xbfb8aa3b, v43
	v_mul_f32_e32 v54, 0xbfb8aa3b, v48
	v_exp_f32_e32 v55, v55
	v_exp_f32_e32 v57, v56
	v_mul_f32_e32 v56, 0xbfb8aa3b, v45
	v_exp_f32_e32 v50, v50
	v_exp_f32_e32 v53, v53
	v_exp_f32_e32 v54, v54
	v_exp_f32_e32 v58, v56
	v_add_f32_e32 v55, 1.0, v55
	v_add_f32_e32 v50, 1.0, v50
	v_add_f32_e32 v53, 1.0, v53
	v_add_f32_e32 v54, 1.0, v54
	v_rcp_f32_e32 v56, v55
	v_add_f32_e32 v55, 1.0, v57
	v_add_f32_e32 v57, 1.0, v58
	v_rcp_f32_e32 v50, v50
	v_rcp_f32_e32 v51, v51
	v_rcp_f32_e32 v54, v54
	v_rcp_f32_e32 v55, v55
	v_rcp_f32_e32 v57, v57
	v_rcp_f32_e32 v53, v53
	v_pk_mul_f32 v[46:47], v[46:47], v[50:51]
	v_pk_mul_f32 v[48:49], v[48:49], v[54:55]
	v_pk_mul_f32 v[44:45], v[44:45], v[56:57]
	v_pk_mul_f32 v[42:43], v[42:43], v[52:53]
.LBB0_152:
	v_cvt_pk_bf16_f32 v46, v46, v47
	v_cvt_pk_bf16_f32 v47, v48, v49
	s_nop 0
	v_cvt_pk_bf16_f32 v48, v42, v43
	v_lshlrev_b64 v[50:51], 13, v[148:149]
	v_lshrrev_b32_e32 v42, 2, v46
	v_and_b32_e32 v42, 0x10001, v42
	v_cvt_pk_bf16_f32 v45, v44, v45
	v_add3_u32 v42, v46, v42, s66
	v_lshrrev_b32_e32 v46, 2, v45
	v_lshl_add_u64 v[50:51], v[150:151], 0, v[50:51]
	v_lshrrev_b32_e32 v43, 2, v47
	v_lshrrev_b32_e32 v44, 2, v48
	v_and_b32_e32 v46, 0x10001, v46
	v_and_b32_e32 v43, 0x10001, v43
	v_and_b32_e32 v44, 0x10001, v44
	v_add3_u32 v45, v45, v46, s66
	v_add_co_u32_e32 v46, vcc, 0x120000, v50
	v_add3_u32 v43, v47, v43, s66
	v_add3_u32 v44, v48, v44, s66
	v_addc_co_u32_e32 v47, vcc, 0, v51, vcc
	v_and_b32_e32 v42, 0xfffcfffc, v42
	v_and_b32_e32 v43, 0xfffcfffc, v43
	v_and_b32_e32 v44, 0xfffcfffc, v44
	v_and_b32_e32 v45, 0xfffcfffc, v45
	s_and_b64 vcc, exec, s[10:11]
	global_store_dwordx4 v[46:47], v[42:45], off sc1
	s_cbranch_vccnz .LBB0_154
	s_nop 0
	v_mul_f32_e32 v43, 0xbfb8aa3b, v34
	v_mul_f32_e32 v44, 0xbfb8aa3b, v39
	v_exp_f32_e32 v43, v43
	v_exp_f32_e32 v45, v44
	v_mul_f32_e32 v47, 0xbfb8aa3b, v36
	v_mul_f32_e32 v48, 0xbfb8aa3b, v41
	v_add_f32_e32 v43, 1.0, v43
	v_mul_f32_e32 v42, 0xbfb8aa3b, v38
	v_rcp_f32_e32 v44, v43
	v_add_f32_e32 v43, 1.0, v45
	v_mul_f32_e32 v45, 0xbfb8aa3b, v35
	v_mul_f32_e32 v46, 0xbfb8aa3b, v40
	v_exp_f32_e32 v47, v47
	v_exp_f32_e32 v49, v48
	v_mul_f32_e32 v48, 0xbfb8aa3b, v37
	v_exp_f32_e32 v42, v42
	v_exp_f32_e32 v45, v45
	v_exp_f32_e32 v46, v46
	v_exp_f32_e32 v52, v48
	v_add_f32_e32 v47, 1.0, v47
	v_add_f32_e32 v42, 1.0, v42
	v_add_f32_e32 v45, 1.0, v45
	v_add_f32_e32 v46, 1.0, v46
	v_rcp_f32_e32 v48, v47
	v_add_f32_e32 v47, 1.0, v49
	v_add_f32_e32 v49, 1.0, v52
	v_rcp_f32_e32 v42, v42
	v_rcp_f32_e32 v43, v43
	v_rcp_f32_e32 v46, v46
	v_rcp_f32_e32 v47, v47
	v_rcp_f32_e32 v49, v49
	v_rcp_f32_e32 v45, v45
	v_pk_mul_f32 v[38:39], v[38:39], v[42:43]
	v_pk_mul_f32 v[40:41], v[40:41], v[46:47]
	v_pk_mul_f32 v[36:37], v[36:37], v[48:49]
	v_pk_mul_f32 v[34:35], v[34:35], v[44:45]
.LBB0_154:
	v_cvt_pk_bf16_f32 v38, v38, v39
	v_cvt_pk_bf16_f32 v39, v40, v41
	s_nop 0
	v_cvt_pk_bf16_f32 v40, v34, v35
	v_cvt_pk_bf16_f32 v37, v36, v37
	v_lshl_add_u64 v[42:43], v[50:51], 0, s[24:25]
	v_lshrrev_b32_e32 v34, 2, v38
	v_and_b32_e32 v34, 0x10001, v34
	v_add3_u32 v34, v38, v34, s66
	v_lshrrev_b32_e32 v35, 2, v39
	v_lshrrev_b32_e32 v36, 2, v40
	v_lshrrev_b32_e32 v38, 2, v37
	v_and_b32_e32 v35, 0x10001, v35
	v_and_b32_e32 v36, 0x10001, v36
	v_and_b32_e32 v38, 0x10001, v38
	v_add3_u32 v35, v39, v35, s66
	v_add3_u32 v36, v40, v36, s66
	v_add3_u32 v37, v37, v38, s66
	v_and_b32_e32 v34, 0xfffcfffc, v34
	v_and_b32_e32 v35, 0xfffcfffc, v35
	v_and_b32_e32 v36, 0xfffcfffc, v36
	v_and_b32_e32 v37, 0xfffcfffc, v37
	s_and_b64 vcc, exec, s[10:11]
	global_store_dwordx4 v[42:43], v[34:37], off offset:256 sc1
	s_cbranch_vccnz .LBB0_156
	s_nop 0
	v_mul_f32_e32 v35, 0xbfb8aa3b, v26
	v_mul_f32_e32 v36, 0xbfb8aa3b, v31
	v_exp_f32_e32 v35, v35
	v_exp_f32_e32 v37, v36
	v_mul_f32_e32 v39, 0xbfb8aa3b, v28
	v_mul_f32_e32 v40, 0xbfb8aa3b, v33
	v_add_f32_e32 v35, 1.0, v35
	v_mul_f32_e32 v34, 0xbfb8aa3b, v30
	v_rcp_f32_e32 v36, v35
	v_add_f32_e32 v35, 1.0, v37
	v_mul_f32_e32 v37, 0xbfb8aa3b, v27
	v_mul_f32_e32 v38, 0xbfb8aa3b, v32
	v_exp_f32_e32 v39, v39
	v_exp_f32_e32 v41, v40
	v_mul_f32_e32 v40, 0xbfb8aa3b, v29
	v_exp_f32_e32 v34, v34
	v_exp_f32_e32 v37, v37
	v_exp_f32_e32 v38, v38
	v_exp_f32_e32 v42, v40
	v_add_f32_e32 v39, 1.0, v39
	v_add_f32_e32 v34, 1.0, v34
	v_add_f32_e32 v37, 1.0, v37
	v_add_f32_e32 v38, 1.0, v38
	v_rcp_f32_e32 v40, v39
	v_add_f32_e32 v39, 1.0, v41
	v_add_f32_e32 v41, 1.0, v42
	v_rcp_f32_e32 v34, v34
	v_rcp_f32_e32 v35, v35
	v_rcp_f32_e32 v38, v38
	v_rcp_f32_e32 v39, v39
	v_rcp_f32_e32 v41, v41
	v_rcp_f32_e32 v37, v37
	v_pk_mul_f32 v[30:31], v[30:31], v[34:35]
	v_pk_mul_f32 v[32:33], v[32:33], v[38:39]
	v_pk_mul_f32 v[28:29], v[28:29], v[40:41]
	v_pk_mul_f32 v[26:27], v[26:27], v[36:37]
.LBB0_156:
	v_cvt_pk_bf16_f32 v30, v30, v31
	v_cvt_pk_bf16_f32 v31, v32, v33
	s_nop 0
	v_cvt_pk_bf16_f32 v32, v26, v27
	v_lshlrev_b64 v[34:35], 13, v[148:149]
	v_lshrrev_b32_e32 v26, 2, v30
	v_and_b32_e32 v26, 0x10001, v26
	v_cvt_pk_bf16_f32 v29, v28, v29
	v_add3_u32 v26, v30, v26, s66
	v_lshrrev_b32_e32 v30, 2, v29
	v_lshl_add_u64 v[34:35], v[150:151], 0, v[34:35]
	v_lshrrev_b32_e32 v27, 2, v31
	v_lshrrev_b32_e32 v28, 2, v32
	v_and_b32_e32 v30, 0x10001, v30
	v_and_b32_e32 v27, 0x10001, v27
	v_and_b32_e32 v28, 0x10001, v28
	v_add3_u32 v29, v29, v30, s66
	v_add_co_u32_e32 v30, vcc, 0x140000, v34
	v_add3_u32 v27, v31, v27, s66
	v_add3_u32 v28, v32, v28, s66
	v_addc_co_u32_e32 v31, vcc, 0, v35, vcc
	v_and_b32_e32 v26, 0xfffcfffc, v26
	v_and_b32_e32 v27, 0xfffcfffc, v27
	v_and_b32_e32 v28, 0xfffcfffc, v28
	v_and_b32_e32 v29, 0xfffcfffc, v29
	s_and_b64 vcc, exec, s[10:11]
	global_store_dwordx4 v[30:31], v[26:29], off sc1
	s_cbranch_vccnz .LBB0_158
	s_nop 0
	v_mul_f32_e32 v27, 0xbfb8aa3b, v18
	v_mul_f32_e32 v28, 0xbfb8aa3b, v23
	v_exp_f32_e32 v27, v27
	v_exp_f32_e32 v29, v28
	v_mul_f32_e32 v31, 0xbfb8aa3b, v20
	v_mul_f32_e32 v32, 0xbfb8aa3b, v25
	v_add_f32_e32 v27, 1.0, v27
	v_mul_f32_e32 v26, 0xbfb8aa3b, v22
	v_rcp_f32_e32 v28, v27
	v_add_f32_e32 v27, 1.0, v29
	v_mul_f32_e32 v29, 0xbfb8aa3b, v19
	v_mul_f32_e32 v30, 0xbfb8aa3b, v24
	v_exp_f32_e32 v31, v31
	v_exp_f32_e32 v33, v32
	v_mul_f32_e32 v32, 0xbfb8aa3b, v21
	v_exp_f32_e32 v26, v26
	v_exp_f32_e32 v29, v29
	v_exp_f32_e32 v30, v30
	v_exp_f32_e32 v36, v32
	v_add_f32_e32 v31, 1.0, v31
	v_add_f32_e32 v26, 1.0, v26
	v_add_f32_e32 v29, 1.0, v29
	v_add_f32_e32 v30, 1.0, v30
	v_rcp_f32_e32 v32, v31
	v_add_f32_e32 v31, 1.0, v33
	v_add_f32_e32 v33, 1.0, v36
	v_rcp_f32_e32 v26, v26
	v_rcp_f32_e32 v27, v27
	v_rcp_f32_e32 v30, v30
	v_rcp_f32_e32 v31, v31
	v_rcp_f32_e32 v33, v33
	v_rcp_f32_e32 v29, v29
	v_pk_mul_f32 v[22:23], v[22:23], v[26:27]
	v_pk_mul_f32 v[24:25], v[24:25], v[30:31]
	v_pk_mul_f32 v[20:21], v[20:21], v[32:33]
	v_pk_mul_f32 v[18:19], v[18:19], v[28:29]
.LBB0_158:
	v_cvt_pk_bf16_f32 v22, v22, v23
	v_cvt_pk_bf16_f32 v23, v24, v25
	s_nop 0
	v_cvt_pk_bf16_f32 v24, v18, v19
	v_cvt_pk_bf16_f32 v21, v20, v21
	v_lshl_add_u64 v[26:27], v[34:35], 0, s[26:27]
	v_lshrrev_b32_e32 v18, 2, v22
	v_and_b32_e32 v18, 0x10001, v18
	v_add3_u32 v18, v22, v18, s66
	v_lshrrev_b32_e32 v19, 2, v23
	v_lshrrev_b32_e32 v20, 2, v24
	v_lshrrev_b32_e32 v22, 2, v21
	v_and_b32_e32 v19, 0x10001, v19
	v_and_b32_e32 v20, 0x10001, v20
	v_and_b32_e32 v22, 0x10001, v22
	v_add3_u32 v19, v23, v19, s66
	v_add3_u32 v20, v24, v20, s66
	v_add3_u32 v21, v21, v22, s66
	v_and_b32_e32 v18, 0xfffcfffc, v18
	v_and_b32_e32 v19, 0xfffcfffc, v19
	v_and_b32_e32 v20, 0xfffcfffc, v20
	v_and_b32_e32 v21, 0xfffcfffc, v21
	s_and_b64 vcc, exec, s[10:11]
	global_store_dwordx4 v[26:27], v[18:21], off offset:256 sc1
	s_cbranch_vccnz .LBB0_160
	s_nop 0
	v_mul_f32_e32 v19, 0xbfb8aa3b, v10
	v_mul_f32_e32 v20, 0xbfb8aa3b, v15
	v_exp_f32_e32 v19, v19
	v_exp_f32_e32 v21, v20
	v_mul_f32_e32 v23, 0xbfb8aa3b, v12
	v_mul_f32_e32 v24, 0xbfb8aa3b, v17
	v_add_f32_e32 v19, 1.0, v19
	v_mul_f32_e32 v18, 0xbfb8aa3b, v14
	v_rcp_f32_e32 v20, v19
	v_add_f32_e32 v19, 1.0, v21
	v_mul_f32_e32 v21, 0xbfb8aa3b, v11
	v_mul_f32_e32 v22, 0xbfb8aa3b, v16
	v_exp_f32_e32 v23, v23
	v_exp_f32_e32 v25, v24
	v_mul_f32_e32 v24, 0xbfb8aa3b, v13
	v_exp_f32_e32 v18, v18
	v_exp_f32_e32 v21, v21
	v_exp_f32_e32 v22, v22
	v_exp_f32_e32 v26, v24
	v_add_f32_e32 v23, 1.0, v23
	v_add_f32_e32 v18, 1.0, v18
	v_add_f32_e32 v21, 1.0, v21
	v_add_f32_e32 v22, 1.0, v22
	v_rcp_f32_e32 v24, v23
	v_add_f32_e32 v23, 1.0, v25
	v_add_f32_e32 v25, 1.0, v26
	v_rcp_f32_e32 v18, v18
	v_rcp_f32_e32 v19, v19
	v_rcp_f32_e32 v22, v22
	v_rcp_f32_e32 v23, v23
	v_rcp_f32_e32 v25, v25
	v_rcp_f32_e32 v21, v21
	v_pk_mul_f32 v[14:15], v[14:15], v[18:19]
	v_pk_mul_f32 v[16:17], v[16:17], v[22:23]
	v_pk_mul_f32 v[12:13], v[12:13], v[24:25]
	v_pk_mul_f32 v[10:11], v[10:11], v[20:21]
.LBB0_160:
	v_cvt_pk_bf16_f32 v14, v14, v15
	v_cvt_pk_bf16_f32 v15, v16, v17
	s_nop 0
	v_cvt_pk_bf16_f32 v16, v10, v11
	v_lshlrev_b64 v[18:19], 13, v[148:149]
	v_lshrrev_b32_e32 v10, 2, v14
	v_and_b32_e32 v10, 0x10001, v10
	v_cvt_pk_bf16_f32 v13, v12, v13
	v_add3_u32 v10, v14, v10, s66
	v_lshrrev_b32_e32 v14, 2, v13
	v_lshl_add_u64 v[18:19], v[150:151], 0, v[18:19]
	v_lshrrev_b32_e32 v11, 2, v15
	v_lshrrev_b32_e32 v12, 2, v16
	v_and_b32_e32 v14, 0x10001, v14
	v_and_b32_e32 v11, 0x10001, v11
	v_and_b32_e32 v12, 0x10001, v12
	v_add3_u32 v13, v13, v14, s66
	v_add_co_u32_e32 v14, vcc, 0x160000, v18
	v_add3_u32 v11, v15, v11, s66
	v_add3_u32 v12, v16, v12, s66
	v_addc_co_u32_e32 v15, vcc, 0, v19, vcc
	v_and_b32_e32 v10, 0xfffcfffc, v10
	v_and_b32_e32 v11, 0xfffcfffc, v11
	v_and_b32_e32 v12, 0xfffcfffc, v12
	v_and_b32_e32 v13, 0xfffcfffc, v13
	s_and_b64 vcc, exec, s[10:11]
	global_store_dwordx4 v[14:15], v[10:13], off sc1
	s_cbranch_vccnz .LBB0_162
	s_nop 0
	v_mul_f32_e32 v11, 0xbfb8aa3b, v2
	v_mul_f32_e32 v12, 0xbfb8aa3b, v7
	v_exp_f32_e32 v11, v11
	v_exp_f32_e32 v13, v12
	v_mul_f32_e32 v15, 0xbfb8aa3b, v4
	v_mul_f32_e32 v16, 0xbfb8aa3b, v9
	v_add_f32_e32 v11, 1.0, v11
	v_mul_f32_e32 v10, 0xbfb8aa3b, v6
	v_rcp_f32_e32 v12, v11
	v_add_f32_e32 v11, 1.0, v13
	v_mul_f32_e32 v13, 0xbfb8aa3b, v3
	v_mul_f32_e32 v14, 0xbfb8aa3b, v8
	v_exp_f32_e32 v15, v15
	v_exp_f32_e32 v17, v16
	v_mul_f32_e32 v16, 0xbfb8aa3b, v5
	v_exp_f32_e32 v10, v10
	v_exp_f32_e32 v13, v13
	v_exp_f32_e32 v14, v14
	v_exp_f32_e32 v20, v16
	v_add_f32_e32 v15, 1.0, v15
	v_add_f32_e32 v10, 1.0, v10
	v_add_f32_e32 v13, 1.0, v13
	v_add_f32_e32 v14, 1.0, v14
	v_rcp_f32_e32 v16, v15
	v_add_f32_e32 v15, 1.0, v17
	v_add_f32_e32 v17, 1.0, v20
	v_rcp_f32_e32 v10, v10
	v_rcp_f32_e32 v11, v11
	v_rcp_f32_e32 v14, v14
	v_rcp_f32_e32 v15, v15
	v_rcp_f32_e32 v17, v17
	v_rcp_f32_e32 v13, v13
	v_pk_mul_f32 v[6:7], v[6:7], v[10:11]
	v_pk_mul_f32 v[8:9], v[8:9], v[14:15]
	v_pk_mul_f32 v[4:5], v[4:5], v[16:17]
	v_pk_mul_f32 v[2:3], v[2:3], v[12:13]
.LBB0_162:
	v_cvt_pk_bf16_f32 v6, v6, v7
	v_cvt_pk_bf16_f32 v7, v8, v9
	s_nop 0
	v_cvt_pk_bf16_f32 v8, v2, v3
	v_cvt_pk_bf16_f32 v5, v4, v5
	v_lshl_add_u64 v[10:11], v[18:19], 0, s[28:29]
	v_lshrrev_b32_e32 v2, 2, v6
	v_and_b32_e32 v2, 0x10001, v2
	v_add3_u32 v2, v6, v2, s66
	v_lshrrev_b32_e32 v3, 2, v7
	v_lshrrev_b32_e32 v4, 2, v8
	v_lshrrev_b32_e32 v6, 2, v5
	v_and_b32_e32 v3, 0x10001, v3
	v_and_b32_e32 v4, 0x10001, v4
	v_and_b32_e32 v6, 0x10001, v6
	v_add3_u32 v3, v7, v3, s66
	v_add3_u32 v4, v8, v4, s66
	v_add3_u32 v5, v5, v6, s66
	v_and_b32_e32 v2, 0xfffcfffc, v2
	v_and_b32_e32 v3, 0xfffcfffc, v3
	v_and_b32_e32 v4, 0xfffcfffc, v4
	v_and_b32_e32 v5, 0xfffcfffc, v5
	s_and_b64 vcc, exec, s[8:9]
	s_mov_b64 s[0:1], -1
	global_store_dwordx4 v[10:11], v[2:5], off offset:256 sc1
	s_cbranch_vccnz .LBB0_115
	s_andn2_b64 vcc, exec, s[4:5]
	s_cbranch_vccnz .LBB0_114
	s_barrier
	s_branch .LBB0_114

.LBB0_346:
	s_lshl_b32 s0, s55, 8
	s_ashr_i32 s15, s14, 31
	s_and_b32 s16, s0, 0xf00
	s_lshl_b64 s[0:1], s[14:15], 26
	s_add_u32 s0, s37, s0
	v_or_b32_e32 v130, s16, v160
	v_lshl_add_u32 v152, s54, 8, v158
	s_addc_u32 s1, s44, s1
	v_lshlrev_b32_e32 v130, 1, v130
	v_ashrrev_i32_e32 v153, 31, v152
	v_lshl_add_u64 v[154:155], s[0:1], 0, v[130:131]
	v_lshlrev_b64 v[156:157], 13, v[152:153]
	v_cvt_pk_bf16_f32 v126, v126, v127
	v_cvt_pk_bf16_f32 v127, v128, v129
	v_cvt_pk_bf16_f32 v128, v122, v123
	v_cndmask_b32_e64 v122, 0, 1, s[12:13]
	v_lshl_add_u64 v[156:157], v[154:155], 0, v[156:157]
	v_cmp_ne_u32_e64 s[42:43], 1, v122
	s_andn2_b64 vcc, exec, s[12:13]
	v_cvt_pk_bf16_f32 v129, v124, v125
	global_store_dwordx4 v[156:157], v[126:129], off sc1
	s_cbranch_vccnz .LBB0_348
	v_mul_f32_e32 v123, 0xbfb8aa3b, v114
	v_exp_f32_e32 v123, v123
	v_mul_f32_e32 v122, 0xbfb8aa3b, v118
	v_exp_f32_e32 v122, v122
	v_mul_f32_e32 v127, 0xbfb8aa3b, v116
	v_add_f32_e32 v123, 1.0, v123
	v_rcp_f32_e32 v124, v123
	v_mul_f32_e32 v123, 0xbfb8aa3b, v119
	v_exp_f32_e32 v123, v123
	v_add_f32_e32 v122, 1.0, v122
	v_exp_f32_e32 v127, v127
	v_rcp_f32_e32 v122, v122
	v_add_f32_e32 v123, 1.0, v123
	v_rcp_f32_e32 v123, v123
	v_add_f32_e32 v127, 1.0, v127
	v_mul_f32_e32 v125, 0xbfb8aa3b, v115
	v_mul_f32_e32 v126, 0xbfb8aa3b, v120
	v_rcp_f32_e32 v128, v127
	v_mul_f32_e32 v127, 0xbfb8aa3b, v121
	v_pk_mul_f32 v[118:119], v[118:119], v[122:123]
	v_mul_f32_e32 v122, 0xbfb8aa3b, v117
	v_exp_f32_e32 v125, v125
	v_exp_f32_e32 v126, v126
	v_exp_f32_e32 v127, v127
	v_exp_f32_e32 v122, v122
	v_add_f32_e32 v125, 1.0, v125
	v_add_f32_e32 v126, 1.0, v126
	v_add_f32_e32 v127, 1.0, v127
	v_add_f32_e32 v122, 1.0, v122
	v_rcp_f32_e32 v125, v125
	v_rcp_f32_e32 v126, v126
	v_rcp_f32_e32 v127, v127
	v_rcp_f32_e32 v129, v122
	v_pk_mul_f32 v[114:115], v[114:115], v[124:125]
	v_pk_mul_f32 v[120:121], v[120:121], v[126:127]
	v_pk_mul_f32 v[116:117], v[116:117], v[128:129]
.LBB0_348:
	s_and_b64 vcc, exec, s[42:43]
	v_cvt_pk_bf16_f32 v118, v118, v119
	v_cvt_pk_bf16_f32 v119, v120, v121
	v_cvt_pk_bf16_f32 v120, v114, v115
	v_cvt_pk_bf16_f32 v121, v116, v117
	global_store_dwordx4 v[156:157], v[118:121], off offset:256 sc1
	s_cbranch_vccnz .LBB0_350
	v_mul_f32_e32 v115, 0xbfb8aa3b, v106
	v_exp_f32_e32 v115, v115
	v_mul_f32_e32 v114, 0xbfb8aa3b, v110
	v_exp_f32_e32 v114, v114
	v_mul_f32_e32 v119, 0xbfb8aa3b, v108
	v_add_f32_e32 v115, 1.0, v115
	v_rcp_f32_e32 v116, v115
	v_mul_f32_e32 v115, 0xbfb8aa3b, v111
	v_exp_f32_e32 v115, v115
	v_add_f32_e32 v114, 1.0, v114
	v_exp_f32_e32 v119, v119
	v_rcp_f32_e32 v114, v114
	v_add_f32_e32 v115, 1.0, v115
	v_rcp_f32_e32 v115, v115
	v_add_f32_e32 v119, 1.0, v119
	v_mul_f32_e32 v117, 0xbfb8aa3b, v107
	v_mul_f32_e32 v118, 0xbfb8aa3b, v112
	v_rcp_f32_e32 v120, v119
	v_mul_f32_e32 v119, 0xbfb8aa3b, v113
	v_pk_mul_f32 v[110:111], v[110:111], v[114:115]
	v_mul_f32_e32 v114, 0xbfb8aa3b, v109
	v_exp_f32_e32 v117, v117
	v_exp_f32_e32 v118, v118
	v_exp_f32_e32 v119, v119
	v_exp_f32_e32 v114, v114
	v_add_f32_e32 v117, 1.0, v117
	v_add_f32_e32 v118, 1.0, v118
	v_add_f32_e32 v119, 1.0, v119
	v_add_f32_e32 v114, 1.0, v114
	v_rcp_f32_e32 v117, v117
	v_rcp_f32_e32 v118, v118
	v_rcp_f32_e32 v119, v119
	v_rcp_f32_e32 v121, v114
	v_pk_mul_f32 v[106:107], v[106:107], v[116:117]
	v_pk_mul_f32 v[112:113], v[112:113], v[118:119]
	v_pk_mul_f32 v[108:109], v[108:109], v[120:121]
.LBB0_350:
	v_or_b32_e32 v114, 16, v152
	v_ashrrev_i32_e32 v115, 31, v114
	v_lshlrev_b64 v[114:115], 13, v[114:115]
	v_lshl_add_u64 v[114:115], v[154:155], 0, v[114:115]
	s_and_b64 vcc, exec, s[42:43]
	v_cvt_pk_bf16_f32 v110, v110, v111
	v_cvt_pk_bf16_f32 v111, v112, v113
	v_cvt_pk_bf16_f32 v112, v106, v107
	v_cvt_pk_bf16_f32 v113, v108, v109
	global_store_dwordx4 v[114:115], v[110:113], off sc1
	s_cbranch_vccnz .LBB0_352
	v_mul_f32_e32 v107, 0xbfb8aa3b, v98
	v_exp_f32_e32 v107, v107
	v_mul_f32_e32 v106, 0xbfb8aa3b, v102
	v_exp_f32_e32 v106, v106
	v_mul_f32_e32 v111, 0xbfb8aa3b, v100
	v_add_f32_e32 v107, 1.0, v107
	v_rcp_f32_e32 v108, v107
	v_mul_f32_e32 v107, 0xbfb8aa3b, v103
	v_exp_f32_e32 v107, v107
	v_add_f32_e32 v106, 1.0, v106
	v_exp_f32_e32 v111, v111
	v_rcp_f32_e32 v106, v106
	v_add_f32_e32 v107, 1.0, v107
	v_rcp_f32_e32 v107, v107
	v_add_f32_e32 v111, 1.0, v111
	v_mul_f32_e32 v109, 0xbfb8aa3b, v99
	v_mul_f32_e32 v110, 0xbfb8aa3b, v104
	v_rcp_f32_e32 v112, v111
	v_mul_f32_e32 v111, 0xbfb8aa3b, v105
	v_pk_mul_f32 v[102:103], v[102:103], v[106:107]
	v_mul_f32_e32 v106, 0xbfb8aa3b, v101
	v_exp_f32_e32 v109, v109
	v_exp_f32_e32 v110, v110
	v_exp_f32_e32 v111, v111
	v_exp_f32_e32 v106, v106
	v_add_f32_e32 v109, 1.0, v109
	v_add_f32_e32 v110, 1.0, v110
	v_add_f32_e32 v111, 1.0, v111
	v_add_f32_e32 v106, 1.0, v106
	v_rcp_f32_e32 v109, v109
	v_rcp_f32_e32 v110, v110
	v_rcp_f32_e32 v111, v111
	v_rcp_f32_e32 v113, v106
	v_pk_mul_f32 v[98:99], v[98:99], v[108:109]
	v_pk_mul_f32 v[104:105], v[104:105], v[110:111]
	v_pk_mul_f32 v[100:101], v[100:101], v[112:113]
.LBB0_352:
	s_and_b64 vcc, exec, s[42:43]
	v_cvt_pk_bf16_f32 v102, v102, v103
	v_cvt_pk_bf16_f32 v103, v104, v105
	v_cvt_pk_bf16_f32 v104, v98, v99
	v_cvt_pk_bf16_f32 v105, v100, v101
	global_store_dwordx4 v[114:115], v[102:105], off offset:256 sc1
	s_cbranch_vccnz .LBB0_354
	v_mul_f32_e32 v99, 0xbfb8aa3b, v90
	v_exp_f32_e32 v99, v99
	v_mul_f32_e32 v98, 0xbfb8aa3b, v94
	v_exp_f32_e32 v98, v98
	v_mul_f32_e32 v103, 0xbfb8aa3b, v92
	v_add_f32_e32 v99, 1.0, v99
	v_rcp_f32_e32 v100, v99
	v_mul_f32_e32 v99, 0xbfb8aa3b, v95
	v_exp_f32_e32 v99, v99
	v_add_f32_e32 v98, 1.0, v98
	v_exp_f32_e32 v103, v103
	v_rcp_f32_e32 v98, v98
	v_add_f32_e32 v99, 1.0, v99
	v_rcp_f32_e32 v99, v99
	v_add_f32_e32 v103, 1.0, v103
	v_mul_f32_e32 v101, 0xbfb8aa3b, v91
	v_mul_f32_e32 v102, 0xbfb8aa3b, v96
	v_rcp_f32_e32 v104, v103
	v_mul_f32_e32 v103, 0xbfb8aa3b, v97
	v_pk_mul_f32 v[94:95], v[94:95], v[98:99]
	v_mul_f32_e32 v98, 0xbfb8aa3b, v93
	v_exp_f32_e32 v101, v101
	v_exp_f32_e32 v102, v102
	v_exp_f32_e32 v103, v103
	v_exp_f32_e32 v98, v98
	v_add_f32_e32 v101, 1.0, v101
	v_add_f32_e32 v102, 1.0, v102
	v_add_f32_e32 v103, 1.0, v103
	v_add_f32_e32 v98, 1.0, v98
	v_rcp_f32_e32 v101, v101
	v_rcp_f32_e32 v102, v102
	v_rcp_f32_e32 v103, v103
	v_rcp_f32_e32 v105, v98
	v_pk_mul_f32 v[90:91], v[90:91], v[100:101]
	v_pk_mul_f32 v[96:97], v[96:97], v[102:103]
	v_pk_mul_f32 v[92:93], v[92:93], v[104:105]
.LBB0_354:
	v_or_b32_e32 v98, 32, v152
	v_ashrrev_i32_e32 v99, 31, v98
	v_lshlrev_b64 v[98:99], 13, v[98:99]
	v_lshl_add_u64 v[98:99], v[154:155], 0, v[98:99]
	s_and_b64 vcc, exec, s[42:43]
	v_cvt_pk_bf16_f32 v94, v94, v95
	v_cvt_pk_bf16_f32 v95, v96, v97
	v_cvt_pk_bf16_f32 v96, v90, v91
	v_cvt_pk_bf16_f32 v97, v92, v93
	global_store_dwordx4 v[98:99], v[94:97], off sc1
	s_cbranch_vccnz .LBB0_356
	v_mul_f32_e32 v91, 0xbfb8aa3b, v82
	v_exp_f32_e32 v91, v91
	v_mul_f32_e32 v90, 0xbfb8aa3b, v86
	v_exp_f32_e32 v90, v90
	v_mul_f32_e32 v95, 0xbfb8aa3b, v84
	v_add_f32_e32 v91, 1.0, v91
	v_rcp_f32_e32 v92, v91
	v_mul_f32_e32 v91, 0xbfb8aa3b, v87
	v_exp_f32_e32 v91, v91
	v_add_f32_e32 v90, 1.0, v90
	v_exp_f32_e32 v95, v95
	v_rcp_f32_e32 v90, v90
	v_add_f32_e32 v91, 1.0, v91
	v_rcp_f32_e32 v91, v91
	v_add_f32_e32 v95, 1.0, v95
	v_mul_f32_e32 v93, 0xbfb8aa3b, v83
	v_mul_f32_e32 v94, 0xbfb8aa3b, v88
	v_rcp_f32_e32 v96, v95
	v_mul_f32_e32 v95, 0xbfb8aa3b, v89
	v_pk_mul_f32 v[86:87], v[86:87], v[90:91]
	v_mul_f32_e32 v90, 0xbfb8aa3b, v85
	v_exp_f32_e32 v93, v93
	v_exp_f32_e32 v94, v94
	v_exp_f32_e32 v95, v95
	v_exp_f32_e32 v90, v90
	v_add_f32_e32 v93, 1.0, v93
	v_add_f32_e32 v94, 1.0, v94
	v_add_f32_e32 v95, 1.0, v95
	v_add_f32_e32 v90, 1.0, v90
	v_rcp_f32_e32 v93, v93
	v_rcp_f32_e32 v94, v94
	v_rcp_f32_e32 v95, v95
	v_rcp_f32_e32 v97, v90
	v_pk_mul_f32 v[82:83], v[82:83], v[92:93]
	v_pk_mul_f32 v[88:89], v[88:89], v[94:95]
	v_pk_mul_f32 v[84:85], v[84:85], v[96:97]
.LBB0_356:
	s_and_b64 vcc, exec, s[42:43]
	v_cvt_pk_bf16_f32 v86, v86, v87
	v_cvt_pk_bf16_f32 v87, v88, v89
	v_cvt_pk_bf16_f32 v88, v82, v83
	v_cvt_pk_bf16_f32 v89, v84, v85
	global_store_dwordx4 v[98:99], v[86:89], off offset:256 sc1
	s_cbranch_vccnz .LBB0_358
	v_mul_f32_e32 v83, 0xbfb8aa3b, v74
	v_exp_f32_e32 v83, v83
	v_mul_f32_e32 v82, 0xbfb8aa3b, v78
	v_exp_f32_e32 v82, v82
	v_mul_f32_e32 v87, 0xbfb8aa3b, v76
	v_add_f32_e32 v83, 1.0, v83
	v_rcp_f32_e32 v84, v83
	v_mul_f32_e32 v83, 0xbfb8aa3b, v79
	v_exp_f32_e32 v83, v83
	v_add_f32_e32 v82, 1.0, v82
	v_exp_f32_e32 v87, v87
	v_rcp_f32_e32 v82, v82
	v_add_f32_e32 v83, 1.0, v83
	v_rcp_f32_e32 v83, v83
	v_add_f32_e32 v87, 1.0, v87
	v_mul_f32_e32 v85, 0xbfb8aa3b, v75
	v_mul_f32_e32 v86, 0xbfb8aa3b, v80
	v_rcp_f32_e32 v88, v87
	v_mul_f32_e32 v87, 0xbfb8aa3b, v81
	v_pk_mul_f32 v[78:79], v[78:79], v[82:83]
	v_mul_f32_e32 v82, 0xbfb8aa3b, v77
	v_exp_f32_e32 v85, v85
	v_exp_f32_e32 v86, v86
	v_exp_f32_e32 v87, v87
	v_exp_f32_e32 v82, v82
	v_add_f32_e32 v85, 1.0, v85
	v_add_f32_e32 v86, 1.0, v86
	v_add_f32_e32 v87, 1.0, v87
	v_add_f32_e32 v82, 1.0, v82
	v_rcp_f32_e32 v85, v85
	v_rcp_f32_e32 v86, v86
	v_rcp_f32_e32 v87, v87
	v_rcp_f32_e32 v89, v82
	v_pk_mul_f32 v[74:75], v[74:75], v[84:85]
	v_pk_mul_f32 v[80:81], v[80:81], v[86:87]
	v_pk_mul_f32 v[76:77], v[76:77], v[88:89]
.LBB0_358:
	v_or_b32_e32 v82, 48, v152
	v_ashrrev_i32_e32 v83, 31, v82
	v_lshlrev_b64 v[82:83], 13, v[82:83]
	v_lshl_add_u64 v[82:83], v[154:155], 0, v[82:83]
	s_and_b64 vcc, exec, s[42:43]
	v_cvt_pk_bf16_f32 v78, v78, v79
	v_cvt_pk_bf16_f32 v79, v80, v81
	v_cvt_pk_bf16_f32 v80, v74, v75
	v_cvt_pk_bf16_f32 v81, v76, v77
	global_store_dwordx4 v[82:83], v[78:81], off sc1
	s_cbranch_vccnz .LBB0_360
	v_mul_f32_e32 v75, 0xbfb8aa3b, v66
	v_exp_f32_e32 v75, v75
	v_mul_f32_e32 v74, 0xbfb8aa3b, v70
	v_exp_f32_e32 v74, v74
	v_mul_f32_e32 v79, 0xbfb8aa3b, v68
	v_add_f32_e32 v75, 1.0, v75
	v_rcp_f32_e32 v76, v75
	v_mul_f32_e32 v75, 0xbfb8aa3b, v71
	v_exp_f32_e32 v75, v75
	v_add_f32_e32 v74, 1.0, v74
	v_exp_f32_e32 v79, v79
	v_rcp_f32_e32 v74, v74
	v_add_f32_e32 v75, 1.0, v75
	v_rcp_f32_e32 v75, v75
	v_add_f32_e32 v79, 1.0, v79
	v_mul_f32_e32 v77, 0xbfb8aa3b, v67
	v_mul_f32_e32 v78, 0xbfb8aa3b, v72
	v_rcp_f32_e32 v80, v79
	v_mul_f32_e32 v79, 0xbfb8aa3b, v73
	v_pk_mul_f32 v[70:71], v[70:71], v[74:75]
	v_mul_f32_e32 v74, 0xbfb8aa3b, v69
	v_exp_f32_e32 v77, v77
	v_exp_f32_e32 v78, v78
	v_exp_f32_e32 v79, v79
	v_exp_f32_e32 v74, v74
	v_add_f32_e32 v77, 1.0, v77
	v_add_f32_e32 v78, 1.0, v78
	v_add_f32_e32 v79, 1.0, v79
	v_add_f32_e32 v74, 1.0, v74
	v_rcp_f32_e32 v77, v77
	v_rcp_f32_e32 v78, v78
	v_rcp_f32_e32 v79, v79
	v_rcp_f32_e32 v81, v74
	v_pk_mul_f32 v[66:67], v[66:67], v[76:77]
	v_pk_mul_f32 v[72:73], v[72:73], v[78:79]
	v_pk_mul_f32 v[68:69], v[68:69], v[80:81]
.LBB0_360:
	s_and_b64 vcc, exec, s[42:43]
	v_cvt_pk_bf16_f32 v70, v70, v71
	v_cvt_pk_bf16_f32 v71, v72, v73
	v_cvt_pk_bf16_f32 v72, v66, v67
	v_cvt_pk_bf16_f32 v73, v68, v69
	global_store_dwordx4 v[82:83], v[70:73], off offset:256 sc1
	s_cbranch_vccnz .LBB0_362
	v_mul_f32_e32 v67, 0xbfb8aa3b, v58
	v_exp_f32_e32 v67, v67
	v_mul_f32_e32 v66, 0xbfb8aa3b, v62
	v_exp_f32_e32 v66, v66
	v_mul_f32_e32 v71, 0xbfb8aa3b, v60
	v_add_f32_e32 v67, 1.0, v67
	v_rcp_f32_e32 v68, v67
	v_mul_f32_e32 v67, 0xbfb8aa3b, v63
	v_exp_f32_e32 v67, v67
	v_add_f32_e32 v66, 1.0, v66
	v_exp_f32_e32 v71, v71
	v_rcp_f32_e32 v66, v66
	v_add_f32_e32 v67, 1.0, v67
	v_rcp_f32_e32 v67, v67
	v_add_f32_e32 v71, 1.0, v71
	v_mul_f32_e32 v69, 0xbfb8aa3b, v59
	v_mul_f32_e32 v70, 0xbfb8aa3b, v64
	v_rcp_f32_e32 v72, v71
	v_mul_f32_e32 v71, 0xbfb8aa3b, v65
	v_pk_mul_f32 v[62:63], v[62:63], v[66:67]
	v_mul_f32_e32 v66, 0xbfb8aa3b, v61
	v_exp_f32_e32 v69, v69
	v_exp_f32_e32 v70, v70
	v_exp_f32_e32 v71, v71
	v_exp_f32_e32 v66, v66
	v_add_f32_e32 v69, 1.0, v69
	v_add_f32_e32 v70, 1.0, v70
	v_add_f32_e32 v71, 1.0, v71
	v_add_f32_e32 v66, 1.0, v66
	v_rcp_f32_e32 v69, v69
	v_rcp_f32_e32 v70, v70
	v_rcp_f32_e32 v71, v71
	v_rcp_f32_e32 v73, v66
	v_pk_mul_f32 v[58:59], v[58:59], v[68:69]
	v_pk_mul_f32 v[64:65], v[64:65], v[70:71]
	v_pk_mul_f32 v[60:61], v[60:61], v[72:73]
.LBB0_362:
	v_lshlrev_b64 v[66:67], 13, v[152:153]
	v_lshl_add_u64 v[66:67], v[154:155], 0, v[66:67]
	v_cvt_pk_bf16_f32 v62, v62, v63
	v_cvt_pk_bf16_f32 v63, v64, v65
	v_cvt_pk_bf16_f32 v64, v58, v59
	v_add_co_u32_e32 v58, vcc, 0x100000, v66
	v_cvt_pk_bf16_f32 v65, v60, v61
	s_nop 1
	v_addc_co_u32_e32 v59, vcc, 0, v67, vcc
	s_and_b64 vcc, exec, s[42:43]
	global_store_dwordx4 v[58:59], v[62:65], off sc1
	s_cbranch_vccnz .LBB0_364
	v_mul_f32_e32 v59, 0xbfb8aa3b, v50
	v_exp_f32_e32 v59, v59
	v_mul_f32_e32 v58, 0xbfb8aa3b, v54
	v_exp_f32_e32 v58, v58
	v_mul_f32_e32 v63, 0xbfb8aa3b, v52
	v_add_f32_e32 v59, 1.0, v59
	v_rcp_f32_e32 v60, v59
	v_mul_f32_e32 v59, 0xbfb8aa3b, v55
	v_exp_f32_e32 v59, v59
	v_add_f32_e32 v58, 1.0, v58
	v_exp_f32_e32 v63, v63
	v_rcp_f32_e32 v58, v58
	v_add_f32_e32 v59, 1.0, v59
	v_rcp_f32_e32 v59, v59
	v_add_f32_e32 v63, 1.0, v63
	v_mul_f32_e32 v61, 0xbfb8aa3b, v51
	v_mul_f32_e32 v62, 0xbfb8aa3b, v56
	v_rcp_f32_e32 v64, v63
	v_mul_f32_e32 v63, 0xbfb8aa3b, v57
	v_pk_mul_f32 v[54:55], v[54:55], v[58:59]
	v_mul_f32_e32 v58, 0xbfb8aa3b, v53
	v_exp_f32_e32 v61, v61
	v_exp_f32_e32 v62, v62
	v_exp_f32_e32 v63, v63
	v_exp_f32_e32 v58, v58
	v_add_f32_e32 v61, 1.0, v61
	v_add_f32_e32 v62, 1.0, v62
	v_add_f32_e32 v63, 1.0, v63
	v_add_f32_e32 v58, 1.0, v58
	v_rcp_f32_e32 v61, v61
	v_rcp_f32_e32 v62, v62
	v_rcp_f32_e32 v63, v63
	v_rcp_f32_e32 v65, v58
	v_pk_mul_f32 v[50:51], v[50:51], v[60:61]
	v_pk_mul_f32 v[56:57], v[56:57], v[62:63]
	v_pk_mul_f32 v[52:53], v[52:53], v[64:65]
.LBB0_364:
	s_mov_b64 s[0:1], 0x100000
	v_lshl_add_u64 v[58:59], v[66:67], 0, s[0:1]
	s_and_b64 vcc, exec, s[42:43]
	v_cvt_pk_bf16_f32 v54, v54, v55
	v_cvt_pk_bf16_f32 v55, v56, v57
	v_cvt_pk_bf16_f32 v56, v50, v51
	v_cvt_pk_bf16_f32 v57, v52, v53
	global_store_dwordx4 v[58:59], v[54:57], off offset:256 sc1
	s_cbranch_vccnz .LBB0_366
	v_mul_f32_e32 v51, 0xbfb8aa3b, v42
	v_exp_f32_e32 v51, v51
	v_mul_f32_e32 v50, 0xbfb8aa3b, v46
	v_exp_f32_e32 v50, v50
	v_mul_f32_e32 v55, 0xbfb8aa3b, v44
	v_add_f32_e32 v51, 1.0, v51
	v_rcp_f32_e32 v52, v51
	v_mul_f32_e32 v51, 0xbfb8aa3b, v47
	v_exp_f32_e32 v51, v51
	v_add_f32_e32 v50, 1.0, v50
	v_exp_f32_e32 v55, v55
	v_rcp_f32_e32 v50, v50
	v_add_f32_e32 v51, 1.0, v51
	v_rcp_f32_e32 v51, v51
	v_add_f32_e32 v55, 1.0, v55
	v_mul_f32_e32 v53, 0xbfb8aa3b, v43
	v_mul_f32_e32 v54, 0xbfb8aa3b, v48
	v_rcp_f32_e32 v56, v55
	v_mul_f32_e32 v55, 0xbfb8aa3b, v49
	v_pk_mul_f32 v[46:47], v[46:47], v[50:51]
	v_mul_f32_e32 v50, 0xbfb8aa3b, v45
	v_exp_f32_e32 v53, v53
	v_exp_f32_e32 v54, v54
	v_exp_f32_e32 v55, v55
	v_exp_f32_e32 v50, v50
	v_add_f32_e32 v53, 1.0, v53
	v_add_f32_e32 v54, 1.0, v54
	v_add_f32_e32 v55, 1.0, v55
	v_add_f32_e32 v50, 1.0, v50
	v_rcp_f32_e32 v53, v53
	v_rcp_f32_e32 v54, v54
	v_rcp_f32_e32 v55, v55
	v_rcp_f32_e32 v57, v50
	v_pk_mul_f32 v[42:43], v[42:43], v[52:53]
	v_pk_mul_f32 v[48:49], v[48:49], v[54:55]
	v_pk_mul_f32 v[44:45], v[44:45], v[56:57]
.LBB0_366:
	v_lshlrev_b64 v[50:51], 13, v[152:153]
	v_lshl_add_u64 v[50:51], v[154:155], 0, v[50:51]
	v_cvt_pk_bf16_f32 v46, v46, v47
	v_cvt_pk_bf16_f32 v47, v48, v49
	v_cvt_pk_bf16_f32 v48, v42, v43
	v_add_co_u32_e32 v42, vcc, 0x120000, v50
	v_cvt_pk_bf16_f32 v49, v44, v45
	s_nop 1
	v_addc_co_u32_e32 v43, vcc, 0, v51, vcc
	s_and_b64 vcc, exec, s[42:43]
	global_store_dwordx4 v[42:43], v[46:49], off sc1
	s_cbranch_vccnz .LBB0_368
	v_mul_f32_e32 v43, 0xbfb8aa3b, v34
	v_exp_f32_e32 v43, v43
	v_mul_f32_e32 v42, 0xbfb8aa3b, v38
	v_exp_f32_e32 v42, v42
	v_mul_f32_e32 v47, 0xbfb8aa3b, v36
	v_add_f32_e32 v43, 1.0, v43
	v_rcp_f32_e32 v44, v43
	v_mul_f32_e32 v43, 0xbfb8aa3b, v39
	v_exp_f32_e32 v43, v43
	v_add_f32_e32 v42, 1.0, v42
	v_exp_f32_e32 v47, v47
	v_rcp_f32_e32 v42, v42
	v_add_f32_e32 v43, 1.0, v43
	v_rcp_f32_e32 v43, v43
	v_add_f32_e32 v47, 1.0, v47
	v_mul_f32_e32 v45, 0xbfb8aa3b, v35
	v_mul_f32_e32 v46, 0xbfb8aa3b, v40
	v_rcp_f32_e32 v48, v47
	v_mul_f32_e32 v47, 0xbfb8aa3b, v41
	v_pk_mul_f32 v[38:39], v[38:39], v[42:43]
	v_mul_f32_e32 v42, 0xbfb8aa3b, v37
	v_exp_f32_e32 v45, v45
	v_exp_f32_e32 v46, v46
	v_exp_f32_e32 v47, v47
	v_exp_f32_e32 v42, v42
	v_add_f32_e32 v45, 1.0, v45
	v_add_f32_e32 v46, 1.0, v46
	v_add_f32_e32 v47, 1.0, v47
	v_add_f32_e32 v42, 1.0, v42
	v_rcp_f32_e32 v45, v45
	v_rcp_f32_e32 v46, v46
	v_rcp_f32_e32 v47, v47
	v_rcp_f32_e32 v49, v42
	v_pk_mul_f32 v[34:35], v[34:35], v[44:45]
	v_pk_mul_f32 v[40:41], v[40:41], v[46:47]
	v_pk_mul_f32 v[36:37], v[36:37], v[48:49]
.LBB0_368:
	s_mov_b64 s[0:1], 0x120000
	v_lshl_add_u64 v[42:43], v[50:51], 0, s[0:1]
	s_and_b64 vcc, exec, s[42:43]
	v_cvt_pk_bf16_f32 v38, v38, v39
	v_cvt_pk_bf16_f32 v39, v40, v41
	v_cvt_pk_bf16_f32 v40, v34, v35
	v_cvt_pk_bf16_f32 v41, v36, v37
	global_store_dwordx4 v[42:43], v[38:41], off offset:256 sc1
	s_cbranch_vccnz .LBB0_370
	v_mul_f32_e32 v35, 0xbfb8aa3b, v26
	v_exp_f32_e32 v35, v35
	v_mul_f32_e32 v34, 0xbfb8aa3b, v30
	v_exp_f32_e32 v34, v34
	v_mul_f32_e32 v39, 0xbfb8aa3b, v28
	v_add_f32_e32 v35, 1.0, v35
	v_rcp_f32_e32 v36, v35
	v_mul_f32_e32 v35, 0xbfb8aa3b, v31
	v_exp_f32_e32 v35, v35
	v_add_f32_e32 v34, 1.0, v34
	v_exp_f32_e32 v39, v39
	v_rcp_f32_e32 v34, v34
	v_add_f32_e32 v35, 1.0, v35
	v_rcp_f32_e32 v35, v35
	v_add_f32_e32 v39, 1.0, v39
	v_mul_f32_e32 v37, 0xbfb8aa3b, v27
	v_mul_f32_e32 v38, 0xbfb8aa3b, v32
	v_rcp_f32_e32 v40, v39
	v_mul_f32_e32 v39, 0xbfb8aa3b, v33
	v_pk_mul_f32 v[30:31], v[30:31], v[34:35]
	v_mul_f32_e32 v34, 0xbfb8aa3b, v29
	v_exp_f32_e32 v37, v37
	v_exp_f32_e32 v38, v38
	v_exp_f32_e32 v39, v39
	v_exp_f32_e32 v34, v34
	v_add_f32_e32 v37, 1.0, v37
	v_add_f32_e32 v38, 1.0, v38
	v_add_f32_e32 v39, 1.0, v39
	v_add_f32_e32 v34, 1.0, v34
	v_rcp_f32_e32 v37, v37
	v_rcp_f32_e32 v38, v38
	v_rcp_f32_e32 v39, v39
	v_rcp_f32_e32 v41, v34
	v_pk_mul_f32 v[26:27], v[26:27], v[36:37]
	v_pk_mul_f32 v[32:33], v[32:33], v[38:39]
	v_pk_mul_f32 v[28:29], v[28:29], v[40:41]
.LBB0_370:
	v_lshlrev_b64 v[34:35], 13, v[152:153]
	v_lshl_add_u64 v[34:35], v[154:155], 0, v[34:35]
	v_cvt_pk_bf16_f32 v30, v30, v31
	v_cvt_pk_bf16_f32 v31, v32, v33
	v_cvt_pk_bf16_f32 v32, v26, v27
	v_add_co_u32_e32 v26, vcc, 0x140000, v34
	v_cvt_pk_bf16_f32 v33, v28, v29
	s_nop 1
	v_addc_co_u32_e32 v27, vcc, 0, v35, vcc
	s_and_b64 vcc, exec, s[42:43]
	global_store_dwordx4 v[26:27], v[30:33], off sc1
	s_cbranch_vccnz .LBB0_372
	v_mul_f32_e32 v27, 0xbfb8aa3b, v18
	v_exp_f32_e32 v27, v27
	v_mul_f32_e32 v26, 0xbfb8aa3b, v22
	v_exp_f32_e32 v26, v26
	v_mul_f32_e32 v31, 0xbfb8aa3b, v20
	v_add_f32_e32 v27, 1.0, v27
	v_rcp_f32_e32 v28, v27
	v_mul_f32_e32 v27, 0xbfb8aa3b, v23
	v_exp_f32_e32 v27, v27
	v_add_f32_e32 v26, 1.0, v26
	v_exp_f32_e32 v31, v31
	v_rcp_f32_e32 v26, v26
	v_add_f32_e32 v27, 1.0, v27
	v_rcp_f32_e32 v27, v27
	v_add_f32_e32 v31, 1.0, v31
	v_mul_f32_e32 v29, 0xbfb8aa3b, v19
	v_mul_f32_e32 v30, 0xbfb8aa3b, v24
	v_rcp_f32_e32 v32, v31
	v_mul_f32_e32 v31, 0xbfb8aa3b, v25
	v_pk_mul_f32 v[22:23], v[22:23], v[26:27]
	v_mul_f32_e32 v26, 0xbfb8aa3b, v21
	v_exp_f32_e32 v29, v29
	v_exp_f32_e32 v30, v30
	v_exp_f32_e32 v31, v31
	v_exp_f32_e32 v26, v26
	v_add_f32_e32 v29, 1.0, v29
	v_add_f32_e32 v30, 1.0, v30
	v_add_f32_e32 v31, 1.0, v31
	v_add_f32_e32 v26, 1.0, v26
	v_rcp_f32_e32 v29, v29
	v_rcp_f32_e32 v30, v30
	v_rcp_f32_e32 v31, v31
	v_rcp_f32_e32 v33, v26
	v_pk_mul_f32 v[18:19], v[18:19], v[28:29]
	v_pk_mul_f32 v[24:25], v[24:25], v[30:31]
	v_pk_mul_f32 v[20:21], v[20:21], v[32:33]
.LBB0_372:
	s_mov_b64 s[0:1], 0x140000
	v_lshl_add_u64 v[26:27], v[34:35], 0, s[0:1]
	s_and_b64 vcc, exec, s[42:43]
	v_cvt_pk_bf16_f32 v22, v22, v23
	v_cvt_pk_bf16_f32 v23, v24, v25
	v_cvt_pk_bf16_f32 v24, v18, v19
	v_cvt_pk_bf16_f32 v25, v20, v21
	global_store_dwordx4 v[26:27], v[22:25], off offset:256 sc1
	s_cbranch_vccnz .LBB0_374
	v_mul_f32_e32 v19, 0xbfb8aa3b, v10
	v_exp_f32_e32 v19, v19
	v_mul_f32_e32 v18, 0xbfb8aa3b, v14
	v_exp_f32_e32 v18, v18
	v_mul_f32_e32 v23, 0xbfb8aa3b, v12
	v_add_f32_e32 v19, 1.0, v19
	v_rcp_f32_e32 v20, v19
	v_mul_f32_e32 v19, 0xbfb8aa3b, v15
	v_exp_f32_e32 v19, v19
	v_add_f32_e32 v18, 1.0, v18
	v_exp_f32_e32 v23, v23
	v_rcp_f32_e32 v18, v18
	v_add_f32_e32 v19, 1.0, v19
	v_rcp_f32_e32 v19, v19
	v_add_f32_e32 v23, 1.0, v23
	v_mul_f32_e32 v21, 0xbfb8aa3b, v11
	v_mul_f32_e32 v22, 0xbfb8aa3b, v16
	v_rcp_f32_e32 v24, v23
	v_mul_f32_e32 v23, 0xbfb8aa3b, v17
	v_pk_mul_f32 v[14:15], v[14:15], v[18:19]
	v_mul_f32_e32 v18, 0xbfb8aa3b, v13
	v_exp_f32_e32 v21, v21
	v_exp_f32_e32 v22, v22
	v_exp_f32_e32 v23, v23
	v_exp_f32_e32 v18, v18
	v_add_f32_e32 v21, 1.0, v21
	v_add_f32_e32 v22, 1.0, v22
	v_add_f32_e32 v23, 1.0, v23
	v_add_f32_e32 v18, 1.0, v18
	v_rcp_f32_e32 v21, v21
	v_rcp_f32_e32 v22, v22
	v_rcp_f32_e32 v23, v23
	v_rcp_f32_e32 v25, v18
	v_pk_mul_f32 v[10:11], v[10:11], v[20:21]
	v_pk_mul_f32 v[16:17], v[16:17], v[22:23]
	v_pk_mul_f32 v[12:13], v[12:13], v[24:25]
.LBB0_374:
	v_lshlrev_b64 v[18:19], 13, v[152:153]
	v_lshl_add_u64 v[18:19], v[154:155], 0, v[18:19]
	v_cvt_pk_bf16_f32 v14, v14, v15
	v_cvt_pk_bf16_f32 v15, v16, v17
	v_cvt_pk_bf16_f32 v16, v10, v11
	v_add_co_u32_e32 v10, vcc, 0x160000, v18
	v_cvt_pk_bf16_f32 v17, v12, v13
	s_nop 1
	v_addc_co_u32_e32 v11, vcc, 0, v19, vcc
	s_and_b64 vcc, exec, s[42:43]
	global_store_dwordx4 v[10:11], v[14:17], off sc1
	s_cbranch_vccnz .LBB0_376
	v_mul_f32_e32 v11, 0xbfb8aa3b, v2
	v_exp_f32_e32 v11, v11
	v_mul_f32_e32 v10, 0xbfb8aa3b, v6
	v_exp_f32_e32 v10, v10
	v_mul_f32_e32 v15, 0xbfb8aa3b, v4
	v_add_f32_e32 v11, 1.0, v11
	v_rcp_f32_e32 v12, v11
	v_mul_f32_e32 v11, 0xbfb8aa3b, v7
	v_exp_f32_e32 v11, v11
	v_add_f32_e32 v10, 1.0, v10
	v_exp_f32_e32 v15, v15
	v_rcp_f32_e32 v10, v10
	v_add_f32_e32 v11, 1.0, v11
	v_rcp_f32_e32 v11, v11
	v_add_f32_e32 v15, 1.0, v15
	v_mul_f32_e32 v13, 0xbfb8aa3b, v3
	v_mul_f32_e32 v14, 0xbfb8aa3b, v8
	v_rcp_f32_e32 v16, v15
	v_mul_f32_e32 v15, 0xbfb8aa3b, v9
	v_pk_mul_f32 v[6:7], v[6:7], v[10:11]
	v_mul_f32_e32 v10, 0xbfb8aa3b, v5
	v_exp_f32_e32 v13, v13
	v_exp_f32_e32 v14, v14
	v_exp_f32_e32 v15, v15
	v_exp_f32_e32 v10, v10
	v_add_f32_e32 v13, 1.0, v13
	v_add_f32_e32 v14, 1.0, v14
	v_add_f32_e32 v15, 1.0, v15
	v_add_f32_e32 v10, 1.0, v10
	v_rcp_f32_e32 v13, v13
	v_rcp_f32_e32 v14, v14
	v_rcp_f32_e32 v15, v15
	v_rcp_f32_e32 v17, v10
	v_pk_mul_f32 v[2:3], v[2:3], v[12:13]
	v_pk_mul_f32 v[8:9], v[8:9], v[14:15]
	v_pk_mul_f32 v[4:5], v[4:5], v[16:17]
.LBB0_376:
	s_mov_b64 s[0:1], 0x160000
	v_lshl_add_u64 v[10:11], v[18:19], 0, s[0:1]
	s_and_b64 vcc, exec, s[40:41]
	s_mov_b64 s[0:1], -1
	v_cvt_pk_bf16_f32 v6, v6, v7
	v_cvt_pk_bf16_f32 v7, v8, v9
	v_cvt_pk_bf16_f32 v8, v2, v3
	v_cvt_pk_bf16_f32 v9, v4, v5
	global_store_dwordx4 v[10:11], v[6:9], off offset:256 sc1
	s_cbranch_vccnz .LBB0_329
	s_andn2_b64 vcc, exec, s[10:11]
	s_cbranch_vccnz .LBB0_328
	s_barrier
	s_branch .LBB0_328

.LBB0_577:
	s_lshl_b32 s0, s47, 8
	s_ashr_i32 s15, s14, 31
	s_and_b32 s16, s0, 0xf00
	s_lshl_b64 s[0:1], s[14:15], 26
	s_add_u32 s0, s37, s0
	v_or_b32_e32 v130, s16, v160
	v_lshl_add_u32 v152, s46, 8, v158
	s_addc_u32 s1, s38, s1
	v_lshlrev_b32_e32 v130, 1, v130
	v_ashrrev_i32_e32 v153, 31, v152
	v_lshl_add_u64 v[154:155], s[0:1], 0, v[130:131]
	v_lshlrev_b64 v[156:157], 13, v[152:153]
	v_cvt_pk_bf16_f32 v126, v126, v127
	v_cvt_pk_bf16_f32 v127, v128, v129
	v_cvt_pk_bf16_f32 v128, v122, v123
	v_cndmask_b32_e64 v122, 0, 1, s[12:13]
	v_lshl_add_u64 v[156:157], v[154:155], 0, v[156:157]
	v_cmp_ne_u32_e64 s[42:43], 1, v122
	s_andn2_b64 vcc, exec, s[12:13]
	v_cvt_pk_bf16_f32 v129, v124, v125
	global_store_dwordx4 v[156:157], v[126:129], off sc1
	s_cbranch_vccnz .LBB0_579
	v_mul_f32_e32 v123, 0xbfb8aa3b, v114
	v_exp_f32_e32 v123, v123
	v_mul_f32_e32 v122, 0xbfb8aa3b, v118
	v_exp_f32_e32 v122, v122
	v_mul_f32_e32 v127, 0xbfb8aa3b, v116
	v_add_f32_e32 v123, 1.0, v123
	v_rcp_f32_e32 v124, v123
	v_mul_f32_e32 v123, 0xbfb8aa3b, v119
	v_exp_f32_e32 v123, v123
	v_add_f32_e32 v122, 1.0, v122
	v_exp_f32_e32 v127, v127
	v_rcp_f32_e32 v122, v122
	v_add_f32_e32 v123, 1.0, v123
	v_rcp_f32_e32 v123, v123
	v_add_f32_e32 v127, 1.0, v127
	v_mul_f32_e32 v125, 0xbfb8aa3b, v115
	v_mul_f32_e32 v126, 0xbfb8aa3b, v120
	v_rcp_f32_e32 v128, v127
	v_mul_f32_e32 v127, 0xbfb8aa3b, v121
	v_pk_mul_f32 v[118:119], v[118:119], v[122:123]
	v_mul_f32_e32 v122, 0xbfb8aa3b, v117
	v_exp_f32_e32 v125, v125
	v_exp_f32_e32 v126, v126
	v_exp_f32_e32 v127, v127
	v_exp_f32_e32 v122, v122
	v_add_f32_e32 v125, 1.0, v125
	v_add_f32_e32 v126, 1.0, v126
	v_add_f32_e32 v127, 1.0, v127
	v_add_f32_e32 v122, 1.0, v122
	v_rcp_f32_e32 v125, v125
	v_rcp_f32_e32 v126, v126
	v_rcp_f32_e32 v127, v127
	v_rcp_f32_e32 v129, v122
	v_pk_mul_f32 v[114:115], v[114:115], v[124:125]
	v_pk_mul_f32 v[120:121], v[120:121], v[126:127]
	v_pk_mul_f32 v[116:117], v[116:117], v[128:129]

.LBB0_607:
	s_mov_b64 s[0:1], 0x160000
	v_lshl_add_u64 v[10:11], v[18:19], 0, s[0:1]
	s_and_b64 vcc, exec, s[40:41]
	s_mov_b64 s[0:1], -1
	v_cvt_pk_bf16_f32 v6, v6, v7
	v_cvt_pk_bf16_f32 v7, v8, v9
	v_cvt_pk_bf16_f32 v8, v2, v3
	v_cvt_pk_bf16_f32 v9, v4, v5
	global_store_dwordx4 v[10:11], v[6:9], off offset:256 sc1
	s_cbranch_vccnz .LBB0_560
	s_andn2_b64 vcc, exec, s[4:5]
	s_cbranch_vccnz .LBB0_559
	s_barrier
	s_branch .LBB0_559

.LBB0_887:
	s_lshl_b32 s0, s30, 8
	s_ashr_i32 s39, s38, 31
	s_and_b32 s12, s0, 0xf00
	s_lshl_b64 s[0:1], s[38:39], 26
	s_add_u32 s0, s96, s0
	v_or_b32_e32 v2, s12, v156
	v_lshl_add_u32 v124, s28, 8, v154
	s_addc_u32 s1, s97, s1
	v_lshlrev_b32_e32 v2, 1, v2
	v_ashrrev_i32_e32 v125, 31, v124
	v_mov_b32_e32 v147, v146
	v_lshl_add_u64 v[126:127], s[0:1], 0, v[2:3]
	v_lshlrev_b64 v[128:129], 13, v[124:125]
	v_cvt_pk_bf16_f32 v150, v150, v151
	v_cvt_pk_bf16_f32 v151, v130, v131
	v_mov_b32_e32 v130, v146
	v_mov_b32_e32 v131, v146
	v_cndmask_b32_e64 v2, 0, 1, s[10:11]
	v_lshl_add_u64 v[128:129], v[126:127], 0, v[128:129]
	v_pk_mul_f32 v[122:123], v[130:131], v[122:123]
	v_pk_mul_f32 v[120:121], v[146:147], v[120:121]
	v_pk_mul_f32 v[118:119], v[130:131], v[118:119]
	v_cmp_ne_u32_e64 s[42:43], 1, v2
	s_andn2_b64 vcc, exec, s[10:11]
	v_pk_mul_f32 v[116:117], v[146:147], v[116:117]
	v_cvt_pk_bf16_f32 v152, v152, v153
	v_cvt_pk_bf16_f32 v153, v148, v149
	global_store_dwordx4 v[128:129], v[150:153], off sc1
	s_cbranch_vccnz .LBB0_889
	v_mul_f32_e32 v2, 0xbfb8aa3b, v120
	v_exp_f32_e32 v2, v2
	s_nop 0
	v_add_f32_e32 v2, 1.0, v2
	v_rcp_f32_e32 v148, v2
	v_mul_f32_e32 v2, 0xbfb8aa3b, v116
	v_exp_f32_e32 v2, v2
	s_nop 0
	v_add_f32_e32 v2, 1.0, v2
	v_rcp_f32_e32 v150, v2
	v_mul_f32_e32 v2, 0xbfb8aa3b, v121
	v_exp_f32_e32 v2, v2
	s_nop 0
	v_add_f32_e32 v2, 1.0, v2
	v_rcp_f32_e32 v149, v2
	v_mul_f32_e32 v2, 0xbfb8aa3b, v117
	v_exp_f32_e32 v2, v2
	v_pk_mul_f32 v[120:121], v[120:121], v[148:149]
	v_add_f32_e32 v2, 1.0, v2
	v_rcp_f32_e32 v151, v2
	v_mul_f32_e32 v2, 0xbfb8aa3b, v122
	v_exp_f32_e32 v2, v2
	v_pk_mul_f32 v[116:117], v[116:117], v[150:151]
	v_add_f32_e32 v2, 1.0, v2
	v_rcp_f32_e32 v152, v2
	v_mul_f32_e32 v2, 0xbfb8aa3b, v118
	v_exp_f32_e32 v2, v2
	s_nop 0
	v_add_f32_e32 v2, 1.0, v2
	v_rcp_f32_e32 v158, v2
	v_mul_f32_e32 v2, 0xbfb8aa3b, v123
	v_exp_f32_e32 v2, v2
	s_nop 0
	v_add_f32_e32 v2, 1.0, v2
	v_rcp_f32_e32 v153, v2
	v_mul_f32_e32 v2, 0xbfb8aa3b, v119
	v_exp_f32_e32 v2, v2
	v_pk_mul_f32 v[122:123], v[122:123], v[152:153]
	v_add_f32_e32 v2, 1.0, v2
	v_rcp_f32_e32 v159, v2
	s_nop 0
	v_pk_mul_f32 v[118:119], v[118:119], v[158:159]
.LBB0_889:
	v_cvt_pk_bf16_f32 v120, v120, v121
	v_cvt_pk_bf16_f32 v121, v122, v123
	v_cvt_pk_bf16_f32 v122, v116, v117
	v_pk_mul_f32 v[114:115], v[130:131], v[114:115]
	v_pk_mul_f32 v[112:113], v[146:147], v[112:113]
	v_pk_mul_f32 v[110:111], v[130:131], v[110:111]
	s_and_b64 vcc, exec, s[42:43]
	v_pk_mul_f32 v[116:117], v[146:147], v[108:109]
	v_cvt_pk_bf16_f32 v123, v118, v119
	global_store_dwordx4 v[128:129], v[120:123], off offset:256 sc1
	s_cbranch_vccnz .LBB0_891
	v_mul_f32_e32 v2, 0xbfb8aa3b, v112
	v_exp_f32_e32 v2, v2
	s_nop 0
	v_add_f32_e32 v2, 1.0, v2
	v_rcp_f32_e32 v108, v2
	v_mul_f32_e32 v2, 0xbfb8aa3b, v116
	v_exp_f32_e32 v2, v2
	s_nop 0
	v_add_f32_e32 v2, 1.0, v2
	v_rcp_f32_e32 v118, v2
	v_mul_f32_e32 v2, 0xbfb8aa3b, v113
	v_exp_f32_e32 v2, v2
	s_nop 0
	v_add_f32_e32 v2, 1.0, v2
	v_rcp_f32_e32 v109, v2
	v_mul_f32_e32 v2, 0xbfb8aa3b, v117
	v_exp_f32_e32 v2, v2
	v_pk_mul_f32 v[112:113], v[112:113], v[108:109]
	v_add_f32_e32 v2, 1.0, v2
	v_rcp_f32_e32 v119, v2
	v_mul_f32_e32 v2, 0xbfb8aa3b, v114
	v_exp_f32_e32 v2, v2
	v_pk_mul_f32 v[116:117], v[116:117], v[118:119]
	v_add_f32_e32 v2, 1.0, v2
	v_rcp_f32_e32 v120, v2
	v_mul_f32_e32 v2, 0xbfb8aa3b, v110
	v_exp_f32_e32 v2, v2
	s_nop 0
	v_add_f32_e32 v2, 1.0, v2
	v_rcp_f32_e32 v122, v2
	v_mul_f32_e32 v2, 0xbfb8aa3b, v115
	v_exp_f32_e32 v2, v2
	s_nop 0
	v_add_f32_e32 v2, 1.0, v2
	v_rcp_f32_e32 v121, v2
	v_mul_f32_e32 v2, 0xbfb8aa3b, v111
	v_exp_f32_e32 v2, v2
	v_pk_mul_f32 v[114:115], v[114:115], v[120:121]
	v_add_f32_e32 v2, 1.0, v2
	v_rcp_f32_e32 v123, v2
	s_nop 0
	v_pk_mul_f32 v[110:111], v[110:111], v[122:123]
.LBB0_891:
	v_or_b32_e32 v108, 16, v124
	v_ashrrev_i32_e32 v109, 31, v108
	v_lshlrev_b64 v[108:109], 13, v[108:109]
	v_cvt_pk_bf16_f32 v112, v112, v113
	v_cvt_pk_bf16_f32 v113, v114, v115
	v_cvt_pk_bf16_f32 v114, v116, v117
	v_cvt_pk_bf16_f32 v115, v110, v111
	v_mov_b32_e32 v110, v146
	v_mov_b32_e32 v111, v146
	v_lshl_add_u64 v[108:109], v[126:127], 0, v[108:109]
	v_pk_mul_f32 v[106:107], v[110:111], v[106:107]
	v_pk_mul_f32 v[104:105], v[146:147], v[104:105]
	v_pk_mul_f32 v[102:103], v[110:111], v[102:103]
	s_and_b64 vcc, exec, s[42:43]
	v_pk_mul_f32 v[100:101], v[146:147], v[100:101]
	global_store_dwordx4 v[108:109], v[112:115], off sc1
	s_cbranch_vccnz .LBB0_893
	v_mul_f32_e32 v2, 0xbfb8aa3b, v104
	v_exp_f32_e32 v2, v2
	s_nop 0
	v_add_f32_e32 v2, 1.0, v2
	v_rcp_f32_e32 v112, v2
	v_mul_f32_e32 v2, 0xbfb8aa3b, v100
	v_exp_f32_e32 v2, v2
	s_nop 0
	v_add_f32_e32 v2, 1.0, v2
	v_rcp_f32_e32 v114, v2
	v_mul_f32_e32 v2, 0xbfb8aa3b, v105
	v_exp_f32_e32 v2, v2
	s_nop 0
	v_add_f32_e32 v2, 1.0, v2
	v_rcp_f32_e32 v113, v2
	v_mul_f32_e32 v2, 0xbfb8aa3b, v101
	v_exp_f32_e32 v2, v2
	v_pk_mul_f32 v[104:105], v[104:105], v[112:113]
	v_add_f32_e32 v2, 1.0, v2
	v_rcp_f32_e32 v115, v2
	v_mul_f32_e32 v2, 0xbfb8aa3b, v106
	v_exp_f32_e32 v2, v2
	v_pk_mul_f32 v[100:101], v[100:101], v[114:115]
	v_add_f32_e32 v2, 1.0, v2
	v_rcp_f32_e32 v116, v2
	v_mul_f32_e32 v2, 0xbfb8aa3b, v102
	v_exp_f32_e32 v2, v2
	s_nop 0
	v_add_f32_e32 v2, 1.0, v2
	v_rcp_f32_e32 v118, v2
	v_mul_f32_e32 v2, 0xbfb8aa3b, v107
	v_exp_f32_e32 v2, v2
	s_nop 0
	v_add_f32_e32 v2, 1.0, v2
	v_rcp_f32_e32 v117, v2
	v_mul_f32_e32 v2, 0xbfb8aa3b, v103
	v_exp_f32_e32 v2, v2
	v_pk_mul_f32 v[106:107], v[106:107], v[116:117]
	v_add_f32_e32 v2, 1.0, v2
	v_rcp_f32_e32 v119, v2
	s_nop 0
	v_pk_mul_f32 v[102:103], v[102:103], v[118:119]
.LBB0_893:
	v_cvt_pk_bf16_f32 v104, v104, v105
	v_cvt_pk_bf16_f32 v105, v106, v107
	v_cvt_pk_bf16_f32 v106, v100, v101
	v_pk_mul_f32 v[98:99], v[110:111], v[98:99]
	v_pk_mul_f32 v[96:97], v[146:147], v[96:97]
	v_pk_mul_f32 v[94:95], v[110:111], v[94:95]
	s_and_b64 vcc, exec, s[42:43]
	v_pk_mul_f32 v[100:101], v[146:147], v[92:93]
	v_cvt_pk_bf16_f32 v107, v102, v103
	global_store_dwordx4 v[108:109], v[104:107], off offset:256 sc1
	s_cbranch_vccnz .LBB0_895
	v_mul_f32_e32 v2, 0xbfb8aa3b, v96
	v_exp_f32_e32 v2, v2
	s_nop 0
	v_add_f32_e32 v2, 1.0, v2
	v_rcp_f32_e32 v92, v2
	v_mul_f32_e32 v2, 0xbfb8aa3b, v100
	v_exp_f32_e32 v2, v2
	s_nop 0
	v_add_f32_e32 v2, 1.0, v2
	v_rcp_f32_e32 v102, v2
	v_mul_f32_e32 v2, 0xbfb8aa3b, v97
	v_exp_f32_e32 v2, v2
	s_nop 0
	v_add_f32_e32 v2, 1.0, v2
	v_rcp_f32_e32 v93, v2
	v_mul_f32_e32 v2, 0xbfb8aa3b, v101
	v_exp_f32_e32 v2, v2
	v_pk_mul_f32 v[96:97], v[96:97], v[92:93]
	v_add_f32_e32 v2, 1.0, v2
	v_rcp_f32_e32 v103, v2
	v_mul_f32_e32 v2, 0xbfb8aa3b, v98
	v_exp_f32_e32 v2, v2
	v_pk_mul_f32 v[100:101], v[100:101], v[102:103]
	v_add_f32_e32 v2, 1.0, v2
	v_rcp_f32_e32 v104, v2
	v_mul_f32_e32 v2, 0xbfb8aa3b, v94
	v_exp_f32_e32 v2, v2
	s_nop 0
	v_add_f32_e32 v2, 1.0, v2
	v_rcp_f32_e32 v106, v2
	v_mul_f32_e32 v2, 0xbfb8aa3b, v99
	v_exp_f32_e32 v2, v2
	s_nop 0
	v_add_f32_e32 v2, 1.0, v2
	v_rcp_f32_e32 v105, v2
	v_mul_f32_e32 v2, 0xbfb8aa3b, v95
	v_exp_f32_e32 v2, v2
	v_pk_mul_f32 v[98:99], v[98:99], v[104:105]
	v_add_f32_e32 v2, 1.0, v2
	v_rcp_f32_e32 v107, v2
	s_nop 0
	v_pk_mul_f32 v[94:95], v[94:95], v[106:107]
.LBB0_895:
	v_or_b32_e32 v92, 32, v124
	v_ashrrev_i32_e32 v93, 31, v92
	v_lshlrev_b64 v[92:93], 13, v[92:93]
	v_cvt_pk_bf16_f32 v96, v96, v97
	v_cvt_pk_bf16_f32 v97, v98, v99
	v_cvt_pk_bf16_f32 v98, v100, v101
	v_cvt_pk_bf16_f32 v99, v94, v95
	v_mov_b32_e32 v94, v146
	v_mov_b32_e32 v95, v146
	v_lshl_add_u64 v[92:93], v[126:127], 0, v[92:93]
	v_pk_mul_f32 v[90:91], v[94:95], v[90:91]
	v_pk_mul_f32 v[88:89], v[146:147], v[88:89]
	v_pk_mul_f32 v[86:87], v[94:95], v[86:87]
	s_and_b64 vcc, exec, s[42:43]
	v_pk_mul_f32 v[84:85], v[146:147], v[84:85]
	global_store_dwordx4 v[92:93], v[96:99], off sc1
	s_cbranch_vccnz .LBB0_897
	v_mul_f32_e32 v2, 0xbfb8aa3b, v88
	v_exp_f32_e32 v2, v2
	s_nop 0
	v_add_f32_e32 v2, 1.0, v2
	v_rcp_f32_e32 v96, v2
	v_mul_f32_e32 v2, 0xbfb8aa3b, v84
	v_exp_f32_e32 v2, v2
	s_nop 0
	v_add_f32_e32 v2, 1.0, v2
	v_rcp_f32_e32 v98, v2
	v_mul_f32_e32 v2, 0xbfb8aa3b, v89
	v_exp_f32_e32 v2, v2
	s_nop 0
	v_add_f32_e32 v2, 1.0, v2
	v_rcp_f32_e32 v97, v2
	v_mul_f32_e32 v2, 0xbfb8aa3b, v85
	v_exp_f32_e32 v2, v2
	v_pk_mul_f32 v[88:89], v[88:89], v[96:97]
	v_add_f32_e32 v2, 1.0, v2
	v_rcp_f32_e32 v99, v2
	v_mul_f32_e32 v2, 0xbfb8aa3b, v90
	v_exp_f32_e32 v2, v2
	v_pk_mul_f32 v[84:85], v[84:85], v[98:99]
	v_add_f32_e32 v2, 1.0, v2
	v_rcp_f32_e32 v100, v2
	v_mul_f32_e32 v2, 0xbfb8aa3b, v86
	v_exp_f32_e32 v2, v2
	s_nop 0
	v_add_f32_e32 v2, 1.0, v2
	v_rcp_f32_e32 v102, v2
	v_mul_f32_e32 v2, 0xbfb8aa3b, v91
	v_exp_f32_e32 v2, v2
	s_nop 0
	v_add_f32_e32 v2, 1.0, v2
	v_rcp_f32_e32 v101, v2
	v_mul_f32_e32 v2, 0xbfb8aa3b, v87
	v_exp_f32_e32 v2, v2
	v_pk_mul_f32 v[90:91], v[90:91], v[100:101]
	v_add_f32_e32 v2, 1.0, v2
	v_rcp_f32_e32 v103, v2
	s_nop 0
	v_pk_mul_f32 v[86:87], v[86:87], v[102:103]
.LBB0_897:
	v_cvt_pk_bf16_f32 v88, v88, v89
	v_cvt_pk_bf16_f32 v89, v90, v91
	v_cvt_pk_bf16_f32 v90, v84, v85
	v_pk_mul_f32 v[82:83], v[94:95], v[82:83]
	v_pk_mul_f32 v[80:81], v[146:147], v[80:81]
	v_pk_mul_f32 v[78:79], v[94:95], v[78:79]
	s_and_b64 vcc, exec, s[42:43]
	v_pk_mul_f32 v[84:85], v[146:147], v[76:77]
	v_cvt_pk_bf16_f32 v91, v86, v87
	global_store_dwordx4 v[92:93], v[88:91], off offset:256 sc1
	s_cbranch_vccnz .LBB0_899
	v_mul_f32_e32 v2, 0xbfb8aa3b, v80
	v_exp_f32_e32 v2, v2
	s_nop 0
	v_add_f32_e32 v2, 1.0, v2
	v_rcp_f32_e32 v76, v2
	v_mul_f32_e32 v2, 0xbfb8aa3b, v84
	v_exp_f32_e32 v2, v2
	s_nop 0
	v_add_f32_e32 v2, 1.0, v2
	v_rcp_f32_e32 v86, v2
	v_mul_f32_e32 v2, 0xbfb8aa3b, v81
	v_exp_f32_e32 v2, v2
	s_nop 0
	v_add_f32_e32 v2, 1.0, v2
	v_rcp_f32_e32 v77, v2
	v_mul_f32_e32 v2, 0xbfb8aa3b, v85
	v_exp_f32_e32 v2, v2
	v_pk_mul_f32 v[80:81], v[80:81], v[76:77]
	v_add_f32_e32 v2, 1.0, v2
	v_rcp_f32_e32 v87, v2
	v_mul_f32_e32 v2, 0xbfb8aa3b, v82
	v_exp_f32_e32 v2, v2
	v_pk_mul_f32 v[84:85], v[84:85], v[86:87]
	v_add_f32_e32 v2, 1.0, v2
	v_rcp_f32_e32 v88, v2
	v_mul_f32_e32 v2, 0xbfb8aa3b, v78
	v_exp_f32_e32 v2, v2
	s_nop 0
	v_add_f32_e32 v2, 1.0, v2
	v_rcp_f32_e32 v90, v2
	v_mul_f32_e32 v2, 0xbfb8aa3b, v83
	v_exp_f32_e32 v2, v2
	s_nop 0
	v_add_f32_e32 v2, 1.0, v2
	v_rcp_f32_e32 v89, v2
	v_mul_f32_e32 v2, 0xbfb8aa3b, v79
	v_exp_f32_e32 v2, v2
	v_pk_mul_f32 v[82:83], v[82:83], v[88:89]
	v_add_f32_e32 v2, 1.0, v2
	v_rcp_f32_e32 v91, v2
	s_nop 0
	v_pk_mul_f32 v[78:79], v[78:79], v[90:91]
.LBB0_899:
	v_or_b32_e32 v76, 48, v124
	v_ashrrev_i32_e32 v77, 31, v76
	v_lshlrev_b64 v[76:77], 13, v[76:77]
	v_cvt_pk_bf16_f32 v80, v80, v81
	v_cvt_pk_bf16_f32 v81, v82, v83
	v_cvt_pk_bf16_f32 v82, v84, v85
	v_cvt_pk_bf16_f32 v83, v78, v79
	v_mov_b32_e32 v78, v146
	v_mov_b32_e32 v79, v146
	v_lshl_add_u64 v[76:77], v[126:127], 0, v[76:77]
	v_pk_mul_f32 v[74:75], v[78:79], v[74:75]
	v_pk_mul_f32 v[72:73], v[146:147], v[72:73]
	v_pk_mul_f32 v[70:71], v[78:79], v[70:71]
	s_and_b64 vcc, exec, s[42:43]
	v_pk_mul_f32 v[68:69], v[146:147], v[68:69]
	global_store_dwordx4 v[76:77], v[80:83], off sc1
	s_cbranch_vccnz .LBB0_901
	v_mul_f32_e32 v2, 0xbfb8aa3b, v72
	v_exp_f32_e32 v2, v2
	s_nop 0
	v_add_f32_e32 v2, 1.0, v2
	v_rcp_f32_e32 v80, v2
	v_mul_f32_e32 v2, 0xbfb8aa3b, v68
	v_exp_f32_e32 v2, v2
	s_nop 0
	v_add_f32_e32 v2, 1.0, v2
	v_rcp_f32_e32 v82, v2
	v_mul_f32_e32 v2, 0xbfb8aa3b, v73
	v_exp_f32_e32 v2, v2
	s_nop 0
	v_add_f32_e32 v2, 1.0, v2
	v_rcp_f32_e32 v81, v2
	v_mul_f32_e32 v2, 0xbfb8aa3b, v69
	v_exp_f32_e32 v2, v2
	v_pk_mul_f32 v[72:73], v[72:73], v[80:81]
	v_add_f32_e32 v2, 1.0, v2
	v_rcp_f32_e32 v83, v2
	v_mul_f32_e32 v2, 0xbfb8aa3b, v74
	v_exp_f32_e32 v2, v2
	v_pk_mul_f32 v[68:69], v[68:69], v[82:83]
	v_add_f32_e32 v2, 1.0, v2
	v_rcp_f32_e32 v84, v2
	v_mul_f32_e32 v2, 0xbfb8aa3b, v70
	v_exp_f32_e32 v2, v2
	s_nop 0
	v_add_f32_e32 v2, 1.0, v2
	v_rcp_f32_e32 v86, v2
	v_mul_f32_e32 v2, 0xbfb8aa3b, v75
	v_exp_f32_e32 v2, v2
	s_nop 0
	v_add_f32_e32 v2, 1.0, v2
	v_rcp_f32_e32 v85, v2
	v_mul_f32_e32 v2, 0xbfb8aa3b, v71
	v_exp_f32_e32 v2, v2
	v_pk_mul_f32 v[74:75], v[74:75], v[84:85]
	v_add_f32_e32 v2, 1.0, v2
	v_rcp_f32_e32 v87, v2
	s_nop 0
	v_pk_mul_f32 v[70:71], v[70:71], v[86:87]
.LBB0_901:
	v_cvt_pk_bf16_f32 v72, v72, v73
	v_cvt_pk_bf16_f32 v73, v74, v75
	v_cvt_pk_bf16_f32 v74, v68, v69
	v_pk_mul_f32 v[66:67], v[78:79], v[66:67]
	v_pk_mul_f32 v[68:69], v[146:147], v[64:65]
	v_pk_mul_f32 v[64:65], v[78:79], v[62:63]
	s_and_b64 vcc, exec, s[42:43]
	v_pk_mul_f32 v[60:61], v[146:147], v[60:61]
	v_cvt_pk_bf16_f32 v75, v70, v71
	global_store_dwordx4 v[76:77], v[72:75], off offset:256 sc1
	s_cbranch_vccnz .LBB0_903
	v_mul_f32_e32 v2, 0xbfb8aa3b, v68
	v_exp_f32_e32 v2, v2
	s_nop 0
	v_add_f32_e32 v2, 1.0, v2
	v_rcp_f32_e32 v62, v2
	v_mul_f32_e32 v2, 0xbfb8aa3b, v60
	v_exp_f32_e32 v2, v2
	s_nop 0
	v_add_f32_e32 v2, 1.0, v2
	v_rcp_f32_e32 v70, v2
	v_mul_f32_e32 v2, 0xbfb8aa3b, v69
	v_exp_f32_e32 v2, v2
	s_nop 0
	v_add_f32_e32 v2, 1.0, v2
	v_rcp_f32_e32 v63, v2
	v_mul_f32_e32 v2, 0xbfb8aa3b, v61
	v_exp_f32_e32 v2, v2
	v_pk_mul_f32 v[68:69], v[68:69], v[62:63]
	v_add_f32_e32 v2, 1.0, v2
	v_rcp_f32_e32 v71, v2
	v_mul_f32_e32 v2, 0xbfb8aa3b, v66
	v_exp_f32_e32 v2, v2
	v_pk_mul_f32 v[60:61], v[60:61], v[70:71]
	v_add_f32_e32 v2, 1.0, v2
	v_rcp_f32_e32 v72, v2
	v_mul_f32_e32 v2, 0xbfb8aa3b, v64
	v_exp_f32_e32 v2, v2
	s_nop 0
	v_add_f32_e32 v2, 1.0, v2
	v_rcp_f32_e32 v74, v2
	v_mul_f32_e32 v2, 0xbfb8aa3b, v67
	v_exp_f32_e32 v2, v2
	s_nop 0
	v_add_f32_e32 v2, 1.0, v2
	v_rcp_f32_e32 v73, v2
	v_mul_f32_e32 v2, 0xbfb8aa3b, v65
	v_exp_f32_e32 v2, v2
	v_pk_mul_f32 v[66:67], v[66:67], v[72:73]
	v_add_f32_e32 v2, 1.0, v2
	v_rcp_f32_e32 v75, v2
	s_nop 0
	v_pk_mul_f32 v[64:65], v[64:65], v[74:75]
.LBB0_903:
	v_lshlrev_b64 v[62:63], 13, v[124:125]
	v_lshl_add_u64 v[62:63], v[126:127], 0, v[62:63]
	s_mov_b32 s0, 0x100000
	v_cvt_pk_bf16_f32 v68, v68, v69
	v_cvt_pk_bf16_f32 v69, v66, v67
	v_cvt_pk_bf16_f32 v70, v60, v61
	v_add_co_u32_e32 v60, vcc, s0, v62
	v_cvt_pk_bf16_f32 v71, v64, v65
	v_pk_mul_f32 v[56:57], v[146:147], v[56:57]
	s_nop 0
	v_addc_co_u32_e32 v61, vcc, 0, v63, vcc
	global_store_dwordx4 v[60:61], v[68:71], off sc1
	v_mov_b32_e32 v60, v146
	v_mov_b32_e32 v61, v146
	v_pk_mul_f32 v[58:59], v[60:61], v[58:59]
	v_pk_mul_f32 v[54:55], v[60:61], v[54:55]
	s_and_b64 vcc, exec, s[42:43]
	v_pk_mul_f32 v[52:53], v[146:147], v[52:53]
	s_cbranch_vccnz .LBB0_905
	v_mul_f32_e32 v2, 0xbfb8aa3b, v56
	v_exp_f32_e32 v2, v2
	s_nop 0
	v_add_f32_e32 v2, 1.0, v2
	v_rcp_f32_e32 v64, v2
	v_mul_f32_e32 v2, 0xbfb8aa3b, v52
	v_exp_f32_e32 v2, v2
	s_nop 0
	v_add_f32_e32 v2, 1.0, v2
	v_rcp_f32_e32 v66, v2
	v_mul_f32_e32 v2, 0xbfb8aa3b, v57
	v_exp_f32_e32 v2, v2
	s_nop 0
	v_add_f32_e32 v2, 1.0, v2
	v_rcp_f32_e32 v65, v2
	v_mul_f32_e32 v2, 0xbfb8aa3b, v53
	v_exp_f32_e32 v2, v2
	v_pk_mul_f32 v[56:57], v[56:57], v[64:65]
	v_add_f32_e32 v2, 1.0, v2
	v_rcp_f32_e32 v67, v2
	v_mul_f32_e32 v2, 0xbfb8aa3b, v58
	v_exp_f32_e32 v2, v2
	v_pk_mul_f32 v[52:53], v[52:53], v[66:67]
	v_add_f32_e32 v2, 1.0, v2
	v_rcp_f32_e32 v68, v2
	v_mul_f32_e32 v2, 0xbfb8aa3b, v54
	v_exp_f32_e32 v2, v2
	s_nop 0
	v_add_f32_e32 v2, 1.0, v2
	v_rcp_f32_e32 v70, v2
	v_mul_f32_e32 v2, 0xbfb8aa3b, v59
	v_exp_f32_e32 v2, v2
	s_nop 0
	v_add_f32_e32 v2, 1.0, v2
	v_rcp_f32_e32 v69, v2
	v_mul_f32_e32 v2, 0xbfb8aa3b, v55
	v_exp_f32_e32 v2, v2
	v_pk_mul_f32 v[58:59], v[58:59], v[68:69]
	v_add_f32_e32 v2, 1.0, v2
	v_rcp_f32_e32 v71, v2
	s_nop 0
	v_pk_mul_f32 v[54:55], v[54:55], v[70:71]
.LBB0_905:
	s_mov_b64 s[0:1], 0x100000
	v_lshl_add_u64 v[62:63], v[62:63], 0, s[0:1]
	v_cvt_pk_bf16_f32 v56, v56, v57
	v_cvt_pk_bf16_f32 v57, v58, v59
	v_cvt_pk_bf16_f32 v58, v52, v53
	v_pk_mul_f32 v[50:51], v[60:61], v[50:51]
	v_pk_mul_f32 v[52:53], v[146:147], v[48:49]
	v_pk_mul_f32 v[48:49], v[60:61], v[46:47]
	s_and_b64 vcc, exec, s[42:43]
	v_pk_mul_f32 v[44:45], v[146:147], v[44:45]
	v_cvt_pk_bf16_f32 v59, v54, v55
	global_store_dwordx4 v[62:63], v[56:59], off offset:256 sc1
	s_cbranch_vccnz .LBB0_907
	v_mul_f32_e32 v2, 0xbfb8aa3b, v52
	v_exp_f32_e32 v2, v2
	s_nop 0
	v_add_f32_e32 v2, 1.0, v2
	v_rcp_f32_e32 v46, v2
	v_mul_f32_e32 v2, 0xbfb8aa3b, v44
	v_exp_f32_e32 v2, v2
	s_nop 0
	v_add_f32_e32 v2, 1.0, v2
	v_rcp_f32_e32 v54, v2
	v_mul_f32_e32 v2, 0xbfb8aa3b, v53
	v_exp_f32_e32 v2, v2
	s_nop 0
	v_add_f32_e32 v2, 1.0, v2
	v_rcp_f32_e32 v47, v2
	v_mul_f32_e32 v2, 0xbfb8aa3b, v45
	v_exp_f32_e32 v2, v2
	v_pk_mul_f32 v[52:53], v[52:53], v[46:47]
	v_add_f32_e32 v2, 1.0, v2
	v_rcp_f32_e32 v55, v2
	v_mul_f32_e32 v2, 0xbfb8aa3b, v50
	v_exp_f32_e32 v2, v2
	v_pk_mul_f32 v[44:45], v[44:45], v[54:55]
	v_add_f32_e32 v2, 1.0, v2
	v_rcp_f32_e32 v56, v2
	v_mul_f32_e32 v2, 0xbfb8aa3b, v48
	v_exp_f32_e32 v2, v2
	s_nop 0
	v_add_f32_e32 v2, 1.0, v2
	v_rcp_f32_e32 v58, v2
	v_mul_f32_e32 v2, 0xbfb8aa3b, v51
	v_exp_f32_e32 v2, v2
	s_nop 0
	v_add_f32_e32 v2, 1.0, v2
	v_rcp_f32_e32 v57, v2
	v_mul_f32_e32 v2, 0xbfb8aa3b, v49
	v_exp_f32_e32 v2, v2
	v_pk_mul_f32 v[50:51], v[50:51], v[56:57]
	v_add_f32_e32 v2, 1.0, v2
	v_rcp_f32_e32 v59, v2
	s_nop 0
	v_pk_mul_f32 v[48:49], v[48:49], v[58:59]
.LBB0_907:
	v_lshlrev_b64 v[46:47], 13, v[124:125]
	v_lshl_add_u64 v[46:47], v[126:127], 0, v[46:47]
	s_mov_b32 s0, 0x120000
	v_cvt_pk_bf16_f32 v52, v52, v53
	v_cvt_pk_bf16_f32 v53, v50, v51
	v_cvt_pk_bf16_f32 v54, v44, v45
	v_add_co_u32_e32 v44, vcc, s0, v46
	v_cvt_pk_bf16_f32 v55, v48, v49
	v_pk_mul_f32 v[40:41], v[146:147], v[40:41]
	s_nop 0
	v_addc_co_u32_e32 v45, vcc, 0, v47, vcc
	global_store_dwordx4 v[44:45], v[52:55], off sc1
	v_mov_b32_e32 v44, v146
	v_mov_b32_e32 v45, v146
	v_pk_mul_f32 v[42:43], v[44:45], v[42:43]
	v_pk_mul_f32 v[38:39], v[44:45], v[38:39]
	s_and_b64 vcc, exec, s[42:43]
	v_pk_mul_f32 v[36:37], v[146:147], v[36:37]
	s_cbranch_vccnz .LBB0_909
	v_mul_f32_e32 v2, 0xbfb8aa3b, v40
	v_exp_f32_e32 v2, v2
	s_nop 0
	v_add_f32_e32 v2, 1.0, v2
	v_rcp_f32_e32 v48, v2
	v_mul_f32_e32 v2, 0xbfb8aa3b, v36
	v_exp_f32_e32 v2, v2
	s_nop 0
	v_add_f32_e32 v2, 1.0, v2
	v_rcp_f32_e32 v50, v2
	v_mul_f32_e32 v2, 0xbfb8aa3b, v41
	v_exp_f32_e32 v2, v2
	s_nop 0
	v_add_f32_e32 v2, 1.0, v2
	v_rcp_f32_e32 v49, v2
	v_mul_f32_e32 v2, 0xbfb8aa3b, v37
	v_exp_f32_e32 v2, v2
	v_pk_mul_f32 v[40:41], v[40:41], v[48:49]
	v_add_f32_e32 v2, 1.0, v2
	v_rcp_f32_e32 v51, v2
	v_mul_f32_e32 v2, 0xbfb8aa3b, v42
	v_exp_f32_e32 v2, v2
	v_pk_mul_f32 v[36:37], v[36:37], v[50:51]
	v_add_f32_e32 v2, 1.0, v2
	v_rcp_f32_e32 v52, v2
	v_mul_f32_e32 v2, 0xbfb8aa3b, v38
	v_exp_f32_e32 v2, v2
	s_nop 0
	v_add_f32_e32 v2, 1.0, v2
	v_rcp_f32_e32 v54, v2
	v_mul_f32_e32 v2, 0xbfb8aa3b, v43
	v_exp_f32_e32 v2, v2
	s_nop 0
	v_add_f32_e32 v2, 1.0, v2
	v_rcp_f32_e32 v53, v2
	v_mul_f32_e32 v2, 0xbfb8aa3b, v39
	v_exp_f32_e32 v2, v2
	v_pk_mul_f32 v[42:43], v[42:43], v[52:53]
	v_add_f32_e32 v2, 1.0, v2
	v_rcp_f32_e32 v55, v2
	s_nop 0
	v_pk_mul_f32 v[38:39], v[38:39], v[54:55]
.LBB0_909:
	s_mov_b64 s[0:1], 0x120000
	v_lshl_add_u64 v[46:47], v[46:47], 0, s[0:1]
	v_cvt_pk_bf16_f32 v40, v40, v41
	v_cvt_pk_bf16_f32 v41, v42, v43
	v_cvt_pk_bf16_f32 v42, v36, v37
	v_pk_mul_f32 v[34:35], v[44:45], v[34:35]
	v_pk_mul_f32 v[36:37], v[146:147], v[32:33]
	v_pk_mul_f32 v[32:33], v[44:45], v[30:31]
	s_and_b64 vcc, exec, s[42:43]
	v_pk_mul_f32 v[28:29], v[146:147], v[28:29]
	v_cvt_pk_bf16_f32 v43, v38, v39
	global_store_dwordx4 v[46:47], v[40:43], off offset:256 sc1
	s_cbranch_vccnz .LBB0_911
	v_mul_f32_e32 v2, 0xbfb8aa3b, v36
	v_exp_f32_e32 v2, v2
	s_nop 0
	v_add_f32_e32 v2, 1.0, v2
	v_rcp_f32_e32 v30, v2
	v_mul_f32_e32 v2, 0xbfb8aa3b, v28
	v_exp_f32_e32 v2, v2
	s_nop 0
	v_add_f32_e32 v2, 1.0, v2
	v_rcp_f32_e32 v38, v2
	v_mul_f32_e32 v2, 0xbfb8aa3b, v37
	v_exp_f32_e32 v2, v2
	s_nop 0
	v_add_f32_e32 v2, 1.0, v2
	v_rcp_f32_e32 v31, v2
	v_mul_f32_e32 v2, 0xbfb8aa3b, v29
	v_exp_f32_e32 v2, v2
	v_pk_mul_f32 v[36:37], v[36:37], v[30:31]
	v_add_f32_e32 v2, 1.0, v2
	v_rcp_f32_e32 v39, v2
	v_mul_f32_e32 v2, 0xbfb8aa3b, v34
	v_exp_f32_e32 v2, v2
	v_pk_mul_f32 v[28:29], v[28:29], v[38:39]
	v_add_f32_e32 v2, 1.0, v2
	v_rcp_f32_e32 v40, v2
	v_mul_f32_e32 v2, 0xbfb8aa3b, v32
	v_exp_f32_e32 v2, v2
	s_nop 0
	v_add_f32_e32 v2, 1.0, v2
	v_rcp_f32_e32 v42, v2
	v_mul_f32_e32 v2, 0xbfb8aa3b, v35
	v_exp_f32_e32 v2, v2
	s_nop 0
	v_add_f32_e32 v2, 1.0, v2
	v_rcp_f32_e32 v41, v2
	v_mul_f32_e32 v2, 0xbfb8aa3b, v33
	v_exp_f32_e32 v2, v2
	v_pk_mul_f32 v[34:35], v[34:35], v[40:41]
	v_add_f32_e32 v2, 1.0, v2
	v_rcp_f32_e32 v43, v2
	s_nop 0
	v_pk_mul_f32 v[32:33], v[32:33], v[42:43]
.LBB0_911:
	v_lshlrev_b64 v[30:31], 13, v[124:125]
	v_lshl_add_u64 v[30:31], v[126:127], 0, v[30:31]
	s_mov_b32 s0, 0x140000
	v_cvt_pk_bf16_f32 v36, v36, v37
	v_cvt_pk_bf16_f32 v37, v34, v35
	v_cvt_pk_bf16_f32 v38, v28, v29
	v_add_co_u32_e32 v28, vcc, s0, v30
	v_cvt_pk_bf16_f32 v39, v32, v33
	v_pk_mul_f32 v[24:25], v[146:147], v[24:25]
	s_nop 0
	v_addc_co_u32_e32 v29, vcc, 0, v31, vcc
	global_store_dwordx4 v[28:29], v[36:39], off sc1
	v_mov_b32_e32 v28, v146
	v_mov_b32_e32 v29, v146
	v_pk_mul_f32 v[26:27], v[28:29], v[26:27]
	v_pk_mul_f32 v[22:23], v[28:29], v[22:23]
	s_and_b64 vcc, exec, s[42:43]
	v_pk_mul_f32 v[20:21], v[146:147], v[20:21]
	s_cbranch_vccnz .LBB0_913
	v_mul_f32_e32 v2, 0xbfb8aa3b, v24
	v_exp_f32_e32 v2, v2
	s_nop 0
	v_add_f32_e32 v2, 1.0, v2
	v_rcp_f32_e32 v32, v2
	v_mul_f32_e32 v2, 0xbfb8aa3b, v20
	v_exp_f32_e32 v2, v2
	s_nop 0
	v_add_f32_e32 v2, 1.0, v2
	v_rcp_f32_e32 v34, v2
	v_mul_f32_e32 v2, 0xbfb8aa3b, v25
	v_exp_f32_e32 v2, v2
	s_nop 0
	v_add_f32_e32 v2, 1.0, v2
	v_rcp_f32_e32 v33, v2
	v_mul_f32_e32 v2, 0xbfb8aa3b, v21
	v_exp_f32_e32 v2, v2
	v_pk_mul_f32 v[24:25], v[24:25], v[32:33]
	v_add_f32_e32 v2, 1.0, v2
	v_rcp_f32_e32 v35, v2
	v_mul_f32_e32 v2, 0xbfb8aa3b, v26
	v_exp_f32_e32 v2, v2
	v_pk_mul_f32 v[20:21], v[20:21], v[34:35]
	v_add_f32_e32 v2, 1.0, v2
	v_rcp_f32_e32 v36, v2
	v_mul_f32_e32 v2, 0xbfb8aa3b, v22
	v_exp_f32_e32 v2, v2
	s_nop 0
	v_add_f32_e32 v2, 1.0, v2
	v_rcp_f32_e32 v38, v2
	v_mul_f32_e32 v2, 0xbfb8aa3b, v27
	v_exp_f32_e32 v2, v2
	s_nop 0
	v_add_f32_e32 v2, 1.0, v2
	v_rcp_f32_e32 v37, v2
	v_mul_f32_e32 v2, 0xbfb8aa3b, v23
	v_exp_f32_e32 v2, v2
	v_pk_mul_f32 v[26:27], v[26:27], v[36:37]
	v_add_f32_e32 v2, 1.0, v2
	v_rcp_f32_e32 v39, v2
	s_nop 0
	v_pk_mul_f32 v[22:23], v[22:23], v[38:39]
.LBB0_913:
	s_mov_b64 s[0:1], 0x140000
	v_lshl_add_u64 v[30:31], v[30:31], 0, s[0:1]
	v_cvt_pk_bf16_f32 v24, v24, v25
	v_cvt_pk_bf16_f32 v25, v26, v27
	v_cvt_pk_bf16_f32 v26, v20, v21
	v_pk_mul_f32 v[18:19], v[28:29], v[18:19]
	v_pk_mul_f32 v[16:17], v[146:147], v[16:17]
	v_pk_mul_f32 v[14:15], v[28:29], v[14:15]
	s_and_b64 vcc, exec, s[42:43]
	v_pk_mul_f32 v[20:21], v[146:147], v[12:13]
	v_cvt_pk_bf16_f32 v27, v22, v23
	global_store_dwordx4 v[30:31], v[24:27], off offset:256 sc1
	s_cbranch_vccnz .LBB0_915
	v_mul_f32_e32 v2, 0xbfb8aa3b, v16
	v_exp_f32_e32 v2, v2
	s_nop 0
	v_add_f32_e32 v2, 1.0, v2
	v_rcp_f32_e32 v12, v2
	v_mul_f32_e32 v2, 0xbfb8aa3b, v20
	v_exp_f32_e32 v2, v2
	s_nop 0
	v_add_f32_e32 v2, 1.0, v2
	v_rcp_f32_e32 v22, v2
	v_mul_f32_e32 v2, 0xbfb8aa3b, v17
	v_exp_f32_e32 v2, v2
	s_nop 0
	v_add_f32_e32 v2, 1.0, v2
	v_rcp_f32_e32 v13, v2
	v_mul_f32_e32 v2, 0xbfb8aa3b, v21
	v_exp_f32_e32 v2, v2
	v_pk_mul_f32 v[16:17], v[16:17], v[12:13]
	v_add_f32_e32 v2, 1.0, v2
	v_rcp_f32_e32 v23, v2
	v_mul_f32_e32 v2, 0xbfb8aa3b, v18
	v_exp_f32_e32 v2, v2
	v_pk_mul_f32 v[20:21], v[20:21], v[22:23]
	v_add_f32_e32 v2, 1.0, v2
	v_rcp_f32_e32 v24, v2
	v_mul_f32_e32 v2, 0xbfb8aa3b, v14
	v_exp_f32_e32 v2, v2
	s_nop 0
	v_add_f32_e32 v2, 1.0, v2
	v_rcp_f32_e32 v26, v2
	v_mul_f32_e32 v2, 0xbfb8aa3b, v19
	v_exp_f32_e32 v2, v2
	s_nop 0
	v_add_f32_e32 v2, 1.0, v2
	v_rcp_f32_e32 v25, v2
	v_mul_f32_e32 v2, 0xbfb8aa3b, v15
	v_exp_f32_e32 v2, v2
	v_pk_mul_f32 v[18:19], v[18:19], v[24:25]
	v_add_f32_e32 v2, 1.0, v2
	v_rcp_f32_e32 v27, v2
	s_nop 0
	v_pk_mul_f32 v[14:15], v[14:15], v[26:27]
.LBB0_915:
	v_lshlrev_b64 v[12:13], 13, v[124:125]
	v_lshl_add_u64 v[12:13], v[126:127], 0, v[12:13]
	s_mov_b32 s0, 0x160000
	v_cvt_pk_bf16_f32 v16, v16, v17
	v_cvt_pk_bf16_f32 v17, v18, v19
	v_cvt_pk_bf16_f32 v18, v20, v21
	v_cvt_pk_bf16_f32 v19, v14, v15
	v_add_co_u32_e32 v14, vcc, s0, v12
	v_pk_mul_f32 v[8:9], v[146:147], v[8:9]
	s_nop 0
	v_addc_co_u32_e32 v15, vcc, 0, v13, vcc
	global_store_dwordx4 v[14:15], v[16:19], off sc1
	v_mov_b32_e32 v14, v146
	v_mov_b32_e32 v15, v146
	v_pk_mul_f32 v[10:11], v[14:15], v[10:11]
	v_pk_mul_f32 v[6:7], v[14:15], v[6:7]
	s_and_b64 vcc, exec, s[42:43]
	v_pk_mul_f32 v[4:5], v[146:147], v[4:5]
	s_cbranch_vccnz .LBB0_917
	v_mul_f32_e32 v2, 0xbfb8aa3b, v8
	v_exp_f32_e32 v2, v2
	s_nop 0
	v_add_f32_e32 v2, 1.0, v2
	v_rcp_f32_e32 v14, v2
	v_mul_f32_e32 v2, 0xbfb8aa3b, v4
	v_exp_f32_e32 v2, v2
	s_nop 0
	v_add_f32_e32 v2, 1.0, v2
	v_rcp_f32_e32 v16, v2
	v_mul_f32_e32 v2, 0xbfb8aa3b, v9
	v_exp_f32_e32 v2, v2
	s_nop 0
	v_add_f32_e32 v2, 1.0, v2
	v_rcp_f32_e32 v15, v2
	v_mul_f32_e32 v2, 0xbfb8aa3b, v5
	v_exp_f32_e32 v2, v2
	v_pk_mul_f32 v[8:9], v[8:9], v[14:15]
	v_add_f32_e32 v2, 1.0, v2
	v_rcp_f32_e32 v17, v2
	v_mul_f32_e32 v2, 0xbfb8aa3b, v10
	v_exp_f32_e32 v2, v2
	v_pk_mul_f32 v[4:5], v[4:5], v[16:17]
	v_add_f32_e32 v2, 1.0, v2
	v_rcp_f32_e32 v18, v2
	v_mul_f32_e32 v2, 0xbfb8aa3b, v6
	v_exp_f32_e32 v2, v2
	s_nop 0
	v_add_f32_e32 v2, 1.0, v2
	v_rcp_f32_e32 v20, v2
	v_mul_f32_e32 v2, 0xbfb8aa3b, v11
	v_exp_f32_e32 v2, v2
	s_nop 0
	v_add_f32_e32 v2, 1.0, v2
	v_rcp_f32_e32 v19, v2
	v_mul_f32_e32 v2, 0xbfb8aa3b, v7
	v_exp_f32_e32 v2, v2
	v_pk_mul_f32 v[10:11], v[10:11], v[18:19]
	v_add_f32_e32 v2, 1.0, v2
	v_rcp_f32_e32 v21, v2
	s_nop 0
	v_pk_mul_f32 v[6:7], v[6:7], v[20:21]
.LBB0_917:
	s_mov_b64 s[0:1], 0x160000
	v_lshl_add_u64 v[12:13], v[12:13], 0, s[0:1]
	s_and_b64 vcc, exec, s[40:41]
	s_mov_b64 s[0:1], -1
	v_cvt_pk_bf16_f32 v8, v8, v9
	v_cvt_pk_bf16_f32 v9, v10, v11
	v_cvt_pk_bf16_f32 v10, v4, v5
	v_cvt_pk_bf16_f32 v11, v6, v7
	global_store_dwordx4 v[12:13], v[8:11], off offset:256 sc1
	s_cbranch_vccnz .LBB0_870
	s_andn2_b64 vcc, exec, s[4:5]
	s_cbranch_vccnz .LBB0_869
	s_barrier
	s_branch .LBB0_869

.LBB0_1231:
	s_lshl_b32 s0, s59, 8
	s_ashr_i32 s29, s28, 31
	s_and_b32 s20, s0, 0xf00
	s_lshl_b64 s[0:1], s[28:29], 26
	s_add_u32 s0, s39, s0
	v_or_b32_e32 v2, s20, v152
	v_lshl_add_u32 v144, s58, 8, v150
	s_addc_u32 s1, s44, s1
	v_lshlrev_b32_e32 v2, 1, v2
	v_ashrrev_i32_e32 v145, 31, v144
	v_lshl_add_u64 v[146:147], s[0:1], 0, v[2:3]
	v_lshlrev_b64 v[148:149], 13, v[144:145]
	v_cndmask_b32_e64 v2, 0, 1, s[10:11]
	v_lshl_add_u64 v[148:149], v[146:147], 0, v[148:149]
	v_cmp_ne_u32_e64 s[42:43], 1, v2
	s_andn2_b64 vcc, exec, s[10:11]
	v_cvt_pk_bf16_f32 v128, v128, v129
	v_cvt_pk_bf16_f32 v129, v130, v131
	v_cvt_pk_bf16_f32 v130, v124, v125
	v_cvt_pk_bf16_f32 v131, v126, v127
	global_store_dwordx4 v[148:149], v[128:131], off sc1
	s_cbranch_vccnz .LBB0_1233
	v_mul_f32_e32 v2, 0xbfb8aa3b, v120
	v_exp_f32_e32 v2, v2
	s_nop 0
	v_add_f32_e32 v2, 1.0, v2
	v_rcp_f32_e32 v124, v2
	v_mul_f32_e32 v2, 0xbfb8aa3b, v116
	v_exp_f32_e32 v2, v2
	s_nop 0
	v_add_f32_e32 v2, 1.0, v2
	v_rcp_f32_e32 v126, v2
	v_mul_f32_e32 v2, 0xbfb8aa3b, v121
	v_exp_f32_e32 v2, v2
	s_nop 0
	v_add_f32_e32 v2, 1.0, v2
	v_rcp_f32_e32 v125, v2
	v_mul_f32_e32 v2, 0xbfb8aa3b, v117
	v_exp_f32_e32 v2, v2
	v_pk_mul_f32 v[120:121], v[120:121], v[124:125]
	v_add_f32_e32 v2, 1.0, v2
	v_rcp_f32_e32 v127, v2
	v_mul_f32_e32 v2, 0xbfb8aa3b, v122
	v_exp_f32_e32 v2, v2
	v_pk_mul_f32 v[116:117], v[116:117], v[126:127]
	v_add_f32_e32 v2, 1.0, v2
	v_rcp_f32_e32 v128, v2
	v_mul_f32_e32 v2, 0xbfb8aa3b, v118
	v_exp_f32_e32 v2, v2
	s_nop 0
	v_add_f32_e32 v2, 1.0, v2
	v_rcp_f32_e32 v130, v2
	v_mul_f32_e32 v2, 0xbfb8aa3b, v123
	v_exp_f32_e32 v2, v2
	s_nop 0
	v_add_f32_e32 v2, 1.0, v2
	v_rcp_f32_e32 v129, v2
	v_mul_f32_e32 v2, 0xbfb8aa3b, v119
	v_exp_f32_e32 v2, v2
	v_pk_mul_f32 v[122:123], v[122:123], v[128:129]
	v_add_f32_e32 v2, 1.0, v2
	v_rcp_f32_e32 v131, v2
	s_nop 0
	v_pk_mul_f32 v[118:119], v[118:119], v[130:131]
.LBB0_1233:
	s_and_b64 vcc, exec, s[42:43]
	v_cvt_pk_bf16_f32 v120, v120, v121
	v_cvt_pk_bf16_f32 v121, v122, v123
	v_cvt_pk_bf16_f32 v122, v116, v117
	v_cvt_pk_bf16_f32 v123, v118, v119
	global_store_dwordx4 v[148:149], v[120:123], off offset:256 sc1
	s_cbranch_vccnz .LBB0_1235
	v_mul_f32_e32 v2, 0xbfb8aa3b, v112
	v_exp_f32_e32 v2, v2
	s_nop 0
	v_add_f32_e32 v2, 1.0, v2
	v_rcp_f32_e32 v116, v2
	v_mul_f32_e32 v2, 0xbfb8aa3b, v108
	v_exp_f32_e32 v2, v2
	s_nop 0
	v_add_f32_e32 v2, 1.0, v2
	v_rcp_f32_e32 v118, v2
	v_mul_f32_e32 v2, 0xbfb8aa3b, v113
	v_exp_f32_e32 v2, v2
	s_nop 0
	v_add_f32_e32 v2, 1.0, v2
	v_rcp_f32_e32 v117, v2
	v_mul_f32_e32 v2, 0xbfb8aa3b, v109
	v_exp_f32_e32 v2, v2
	v_pk_mul_f32 v[112:113], v[112:113], v[116:117]
	v_add_f32_e32 v2, 1.0, v2
	v_rcp_f32_e32 v119, v2
	v_mul_f32_e32 v2, 0xbfb8aa3b, v114
	v_exp_f32_e32 v2, v2
	v_pk_mul_f32 v[108:109], v[108:109], v[118:119]
	v_add_f32_e32 v2, 1.0, v2
	v_rcp_f32_e32 v120, v2
	v_mul_f32_e32 v2, 0xbfb8aa3b, v110
	v_exp_f32_e32 v2, v2
	s_nop 0
	v_add_f32_e32 v2, 1.0, v2
	v_rcp_f32_e32 v122, v2
	v_mul_f32_e32 v2, 0xbfb8aa3b, v115
	v_exp_f32_e32 v2, v2
	s_nop 0
	v_add_f32_e32 v2, 1.0, v2
	v_rcp_f32_e32 v121, v2
	v_mul_f32_e32 v2, 0xbfb8aa3b, v111
	v_exp_f32_e32 v2, v2
	v_pk_mul_f32 v[114:115], v[114:115], v[120:121]
	v_add_f32_e32 v2, 1.0, v2
	v_rcp_f32_e32 v123, v2
	s_nop 0
	v_pk_mul_f32 v[110:111], v[110:111], v[122:123]
.LBB0_1235:
	v_or_b32_e32 v116, 16, v144
	v_ashrrev_i32_e32 v117, 31, v116
	v_lshlrev_b64 v[116:117], 13, v[116:117]
	v_lshl_add_u64 v[116:117], v[146:147], 0, v[116:117]
	s_and_b64 vcc, exec, s[42:43]
	v_cvt_pk_bf16_f32 v112, v112, v113
	v_cvt_pk_bf16_f32 v113, v114, v115
	v_cvt_pk_bf16_f32 v114, v108, v109
	v_cvt_pk_bf16_f32 v115, v110, v111
	global_store_dwordx4 v[116:117], v[112:115], off sc1
	s_cbranch_vccnz .LBB0_1237
	v_mul_f32_e32 v2, 0xbfb8aa3b, v104
	v_exp_f32_e32 v2, v2
	s_nop 0
	v_add_f32_e32 v2, 1.0, v2
	v_rcp_f32_e32 v108, v2
	v_mul_f32_e32 v2, 0xbfb8aa3b, v100
	v_exp_f32_e32 v2, v2
	s_nop 0
	v_add_f32_e32 v2, 1.0, v2
	v_rcp_f32_e32 v110, v2
	v_mul_f32_e32 v2, 0xbfb8aa3b, v105
	v_exp_f32_e32 v2, v2
	s_nop 0
	v_add_f32_e32 v2, 1.0, v2
	v_rcp_f32_e32 v109, v2
	v_mul_f32_e32 v2, 0xbfb8aa3b, v101
	v_exp_f32_e32 v2, v2
	v_pk_mul_f32 v[104:105], v[104:105], v[108:109]
	v_add_f32_e32 v2, 1.0, v2
	v_rcp_f32_e32 v111, v2
	v_mul_f32_e32 v2, 0xbfb8aa3b, v106
	v_exp_f32_e32 v2, v2
	v_pk_mul_f32 v[100:101], v[100:101], v[110:111]
	v_add_f32_e32 v2, 1.0, v2
	v_rcp_f32_e32 v112, v2
	v_mul_f32_e32 v2, 0xbfb8aa3b, v102
	v_exp_f32_e32 v2, v2
	s_nop 0
	v_add_f32_e32 v2, 1.0, v2
	v_rcp_f32_e32 v114, v2
	v_mul_f32_e32 v2, 0xbfb8aa3b, v107
	v_exp_f32_e32 v2, v2
	s_nop 0
	v_add_f32_e32 v2, 1.0, v2
	v_rcp_f32_e32 v113, v2
	v_mul_f32_e32 v2, 0xbfb8aa3b, v103
	v_exp_f32_e32 v2, v2
	v_pk_mul_f32 v[106:107], v[106:107], v[112:113]
	v_add_f32_e32 v2, 1.0, v2
	v_rcp_f32_e32 v115, v2
	s_nop 0
	v_pk_mul_f32 v[102:103], v[102:103], v[114:115]
.LBB0_1237:
	s_and_b64 vcc, exec, s[42:43]
	v_cvt_pk_bf16_f32 v104, v104, v105
	v_cvt_pk_bf16_f32 v105, v106, v107
	v_cvt_pk_bf16_f32 v106, v100, v101
	v_cvt_pk_bf16_f32 v107, v102, v103
	global_store_dwordx4 v[116:117], v[104:107], off offset:256 sc1
	s_cbranch_vccnz .LBB0_1239
	v_mul_f32_e32 v2, 0xbfb8aa3b, v96
	v_exp_f32_e32 v2, v2
	s_nop 0
	v_add_f32_e32 v2, 1.0, v2
	v_rcp_f32_e32 v100, v2
	v_mul_f32_e32 v2, 0xbfb8aa3b, v92
	v_exp_f32_e32 v2, v2
	s_nop 0
	v_add_f32_e32 v2, 1.0, v2
	v_rcp_f32_e32 v102, v2
	v_mul_f32_e32 v2, 0xbfb8aa3b, v97
	v_exp_f32_e32 v2, v2
	s_nop 0
	v_add_f32_e32 v2, 1.0, v2
	v_rcp_f32_e32 v101, v2
	v_mul_f32_e32 v2, 0xbfb8aa3b, v93
	v_exp_f32_e32 v2, v2
	v_pk_mul_f32 v[96:97], v[96:97], v[100:101]
	v_add_f32_e32 v2, 1.0, v2
	v_rcp_f32_e32 v103, v2
	v_mul_f32_e32 v2, 0xbfb8aa3b, v98
	v_exp_f32_e32 v2, v2
	v_pk_mul_f32 v[92:93], v[92:93], v[102:103]
	v_add_f32_e32 v2, 1.0, v2
	v_rcp_f32_e32 v104, v2
	v_mul_f32_e32 v2, 0xbfb8aa3b, v94
	v_exp_f32_e32 v2, v2
	s_nop 0
	v_add_f32_e32 v2, 1.0, v2
	v_rcp_f32_e32 v106, v2
	v_mul_f32_e32 v2, 0xbfb8aa3b, v99
	v_exp_f32_e32 v2, v2
	s_nop 0
	v_add_f32_e32 v2, 1.0, v2
	v_rcp_f32_e32 v105, v2
	v_mul_f32_e32 v2, 0xbfb8aa3b, v95
	v_exp_f32_e32 v2, v2
	v_pk_mul_f32 v[98:99], v[98:99], v[104:105]
	v_add_f32_e32 v2, 1.0, v2
	v_rcp_f32_e32 v107, v2
	s_nop 0
	v_pk_mul_f32 v[94:95], v[94:95], v[106:107]
.LBB0_1239:
	v_or_b32_e32 v100, 32, v144
	v_ashrrev_i32_e32 v101, 31, v100
	v_lshlrev_b64 v[100:101], 13, v[100:101]
	v_lshl_add_u64 v[100:101], v[146:147], 0, v[100:101]
	s_and_b64 vcc, exec, s[42:43]
	v_cvt_pk_bf16_f32 v96, v96, v97
	v_cvt_pk_bf16_f32 v97, v98, v99
	v_cvt_pk_bf16_f32 v98, v92, v93
	v_cvt_pk_bf16_f32 v99, v94, v95
	global_store_dwordx4 v[100:101], v[96:99], off sc1
	s_cbranch_vccnz .LBB0_1241
	v_mul_f32_e32 v2, 0xbfb8aa3b, v88
	v_exp_f32_e32 v2, v2
	s_nop 0
	v_add_f32_e32 v2, 1.0, v2
	v_rcp_f32_e32 v92, v2
	v_mul_f32_e32 v2, 0xbfb8aa3b, v84
	v_exp_f32_e32 v2, v2
	s_nop 0
	v_add_f32_e32 v2, 1.0, v2
	v_rcp_f32_e32 v94, v2
	v_mul_f32_e32 v2, 0xbfb8aa3b, v89
	v_exp_f32_e32 v2, v2
	s_nop 0
	v_add_f32_e32 v2, 1.0, v2
	v_rcp_f32_e32 v93, v2
	v_mul_f32_e32 v2, 0xbfb8aa3b, v85
	v_exp_f32_e32 v2, v2
	v_pk_mul_f32 v[88:89], v[88:89], v[92:93]
	v_add_f32_e32 v2, 1.0, v2
	v_rcp_f32_e32 v95, v2
	v_mul_f32_e32 v2, 0xbfb8aa3b, v90
	v_exp_f32_e32 v2, v2
	v_pk_mul_f32 v[84:85], v[84:85], v[94:95]
	v_add_f32_e32 v2, 1.0, v2
	v_rcp_f32_e32 v96, v2
	v_mul_f32_e32 v2, 0xbfb8aa3b, v86
	v_exp_f32_e32 v2, v2
	s_nop 0
	v_add_f32_e32 v2, 1.0, v2
	v_rcp_f32_e32 v98, v2
	v_mul_f32_e32 v2, 0xbfb8aa3b, v91
	v_exp_f32_e32 v2, v2
	s_nop 0
	v_add_f32_e32 v2, 1.0, v2
	v_rcp_f32_e32 v97, v2
	v_mul_f32_e32 v2, 0xbfb8aa3b, v87
	v_exp_f32_e32 v2, v2
	v_pk_mul_f32 v[90:91], v[90:91], v[96:97]
	v_add_f32_e32 v2, 1.0, v2
	v_rcp_f32_e32 v99, v2
	s_nop 0
	v_pk_mul_f32 v[86:87], v[86:87], v[98:99]
.LBB0_1241:
	s_and_b64 vcc, exec, s[42:43]
	v_cvt_pk_bf16_f32 v88, v88, v89
	v_cvt_pk_bf16_f32 v89, v90, v91
	v_cvt_pk_bf16_f32 v90, v84, v85
	v_cvt_pk_bf16_f32 v91, v86, v87
	global_store_dwordx4 v[100:101], v[88:91], off offset:256 sc1
	s_cbranch_vccnz .LBB0_1243
	v_mul_f32_e32 v2, 0xbfb8aa3b, v80
	v_exp_f32_e32 v2, v2
	s_nop 0
	v_add_f32_e32 v2, 1.0, v2
	v_rcp_f32_e32 v84, v2
	v_mul_f32_e32 v2, 0xbfb8aa3b, v76
	v_exp_f32_e32 v2, v2
	s_nop 0
	v_add_f32_e32 v2, 1.0, v2
	v_rcp_f32_e32 v86, v2
	v_mul_f32_e32 v2, 0xbfb8aa3b, v81
	v_exp_f32_e32 v2, v2
	s_nop 0
	v_add_f32_e32 v2, 1.0, v2
	v_rcp_f32_e32 v85, v2
	v_mul_f32_e32 v2, 0xbfb8aa3b, v77
	v_exp_f32_e32 v2, v2
	v_pk_mul_f32 v[80:81], v[80:81], v[84:85]
	v_add_f32_e32 v2, 1.0, v2
	v_rcp_f32_e32 v87, v2
	v_mul_f32_e32 v2, 0xbfb8aa3b, v82
	v_exp_f32_e32 v2, v2
	v_pk_mul_f32 v[76:77], v[76:77], v[86:87]
	v_add_f32_e32 v2, 1.0, v2
	v_rcp_f32_e32 v88, v2
	v_mul_f32_e32 v2, 0xbfb8aa3b, v78
	v_exp_f32_e32 v2, v2
	s_nop 0
	v_add_f32_e32 v2, 1.0, v2
	v_rcp_f32_e32 v90, v2
	v_mul_f32_e32 v2, 0xbfb8aa3b, v83
	v_exp_f32_e32 v2, v2
	s_nop 0
	v_add_f32_e32 v2, 1.0, v2
	v_rcp_f32_e32 v89, v2
	v_mul_f32_e32 v2, 0xbfb8aa3b, v79
	v_exp_f32_e32 v2, v2
	v_pk_mul_f32 v[82:83], v[82:83], v[88:89]
	v_add_f32_e32 v2, 1.0, v2
	v_rcp_f32_e32 v91, v2
	s_nop 0
	v_pk_mul_f32 v[78:79], v[78:79], v[90:91]
.LBB0_1243:
	v_or_b32_e32 v84, 48, v144
	v_ashrrev_i32_e32 v85, 31, v84
	v_lshlrev_b64 v[84:85], 13, v[84:85]
	v_lshl_add_u64 v[84:85], v[146:147], 0, v[84:85]
	s_and_b64 vcc, exec, s[42:43]
	v_cvt_pk_bf16_f32 v80, v80, v81
	v_cvt_pk_bf16_f32 v81, v82, v83
	v_cvt_pk_bf16_f32 v82, v76, v77
	v_cvt_pk_bf16_f32 v83, v78, v79
	global_store_dwordx4 v[84:85], v[80:83], off sc1
	s_cbranch_vccnz .LBB0_1245
	v_mul_f32_e32 v2, 0xbfb8aa3b, v72
	v_exp_f32_e32 v2, v2
	s_nop 0
	v_add_f32_e32 v2, 1.0, v2
	v_rcp_f32_e32 v76, v2
	v_mul_f32_e32 v2, 0xbfb8aa3b, v68
	v_exp_f32_e32 v2, v2
	s_nop 0
	v_add_f32_e32 v2, 1.0, v2
	v_rcp_f32_e32 v78, v2
	v_mul_f32_e32 v2, 0xbfb8aa3b, v73
	v_exp_f32_e32 v2, v2
	s_nop 0
	v_add_f32_e32 v2, 1.0, v2
	v_rcp_f32_e32 v77, v2
	v_mul_f32_e32 v2, 0xbfb8aa3b, v69
	v_exp_f32_e32 v2, v2
	v_pk_mul_f32 v[72:73], v[72:73], v[76:77]
	v_add_f32_e32 v2, 1.0, v2
	v_rcp_f32_e32 v79, v2
	v_mul_f32_e32 v2, 0xbfb8aa3b, v74
	v_exp_f32_e32 v2, v2
	v_pk_mul_f32 v[68:69], v[68:69], v[78:79]
	v_add_f32_e32 v2, 1.0, v2
	v_rcp_f32_e32 v80, v2
	v_mul_f32_e32 v2, 0xbfb8aa3b, v70
	v_exp_f32_e32 v2, v2
	s_nop 0
	v_add_f32_e32 v2, 1.0, v2
	v_rcp_f32_e32 v82, v2
	v_mul_f32_e32 v2, 0xbfb8aa3b, v75
	v_exp_f32_e32 v2, v2
	s_nop 0
	v_add_f32_e32 v2, 1.0, v2
	v_rcp_f32_e32 v81, v2
	v_mul_f32_e32 v2, 0xbfb8aa3b, v71
	v_exp_f32_e32 v2, v2
	v_pk_mul_f32 v[74:75], v[74:75], v[80:81]
	v_add_f32_e32 v2, 1.0, v2
	v_rcp_f32_e32 v83, v2
	s_nop 0
	v_pk_mul_f32 v[70:71], v[70:71], v[82:83]
.LBB0_1245:
	s_and_b64 vcc, exec, s[42:43]
	v_cvt_pk_bf16_f32 v72, v72, v73
	v_cvt_pk_bf16_f32 v73, v74, v75
	v_cvt_pk_bf16_f32 v74, v68, v69
	v_cvt_pk_bf16_f32 v75, v70, v71
	global_store_dwordx4 v[84:85], v[72:75], off offset:256 sc1
	s_cbranch_vccnz .LBB0_1247
	v_mul_f32_e32 v2, 0xbfb8aa3b, v64
	v_exp_f32_e32 v2, v2
	s_nop 0
	v_add_f32_e32 v2, 1.0, v2
	v_rcp_f32_e32 v68, v2
	v_mul_f32_e32 v2, 0xbfb8aa3b, v60
	v_exp_f32_e32 v2, v2
	s_nop 0
	v_add_f32_e32 v2, 1.0, v2
	v_rcp_f32_e32 v70, v2
	v_mul_f32_e32 v2, 0xbfb8aa3b, v65
	v_exp_f32_e32 v2, v2
	s_nop 0
	v_add_f32_e32 v2, 1.0, v2
	v_rcp_f32_e32 v69, v2
	v_mul_f32_e32 v2, 0xbfb8aa3b, v61
	v_exp_f32_e32 v2, v2
	v_pk_mul_f32 v[64:65], v[64:65], v[68:69]
	v_add_f32_e32 v2, 1.0, v2
	v_rcp_f32_e32 v71, v2
	v_mul_f32_e32 v2, 0xbfb8aa3b, v66
	v_exp_f32_e32 v2, v2
	v_pk_mul_f32 v[60:61], v[60:61], v[70:71]
	v_add_f32_e32 v2, 1.0, v2
	v_rcp_f32_e32 v72, v2
	v_mul_f32_e32 v2, 0xbfb8aa3b, v62
	v_exp_f32_e32 v2, v2
	s_nop 0
	v_add_f32_e32 v2, 1.0, v2
	v_rcp_f32_e32 v74, v2
	v_mul_f32_e32 v2, 0xbfb8aa3b, v67
	v_exp_f32_e32 v2, v2
	s_nop 0
	v_add_f32_e32 v2, 1.0, v2
	v_rcp_f32_e32 v73, v2
	v_mul_f32_e32 v2, 0xbfb8aa3b, v63
	v_exp_f32_e32 v2, v2
	v_pk_mul_f32 v[66:67], v[66:67], v[72:73]
	v_add_f32_e32 v2, 1.0, v2
	v_rcp_f32_e32 v75, v2
	s_nop 0
	v_pk_mul_f32 v[62:63], v[62:63], v[74:75]
.LBB0_1247:
	v_lshlrev_b64 v[68:69], 13, v[144:145]
	v_lshl_add_u64 v[68:69], v[146:147], 0, v[68:69]
	v_cvt_pk_bf16_f32 v64, v64, v65
	v_cvt_pk_bf16_f32 v65, v66, v67
	v_cvt_pk_bf16_f32 v66, v60, v61
	v_add_co_u32_e32 v60, vcc, 0x100000, v68
	v_cvt_pk_bf16_f32 v67, v62, v63
	s_nop 1
	v_addc_co_u32_e32 v61, vcc, 0, v69, vcc
	s_and_b64 vcc, exec, s[42:43]
	global_store_dwordx4 v[60:61], v[64:67], off sc1
	s_cbranch_vccnz .LBB0_1249
	v_mul_f32_e32 v2, 0xbfb8aa3b, v56
	v_exp_f32_e32 v2, v2
	s_nop 0
	v_add_f32_e32 v2, 1.0, v2
	v_rcp_f32_e32 v60, v2
	v_mul_f32_e32 v2, 0xbfb8aa3b, v52
	v_exp_f32_e32 v2, v2
	s_nop 0
	v_add_f32_e32 v2, 1.0, v2
	v_rcp_f32_e32 v62, v2
	v_mul_f32_e32 v2, 0xbfb8aa3b, v57
	v_exp_f32_e32 v2, v2
	s_nop 0
	v_add_f32_e32 v2, 1.0, v2
	v_rcp_f32_e32 v61, v2
	v_mul_f32_e32 v2, 0xbfb8aa3b, v53
	v_exp_f32_e32 v2, v2
	v_pk_mul_f32 v[56:57], v[56:57], v[60:61]
	v_add_f32_e32 v2, 1.0, v2
	v_rcp_f32_e32 v63, v2
	v_mul_f32_e32 v2, 0xbfb8aa3b, v58
	v_exp_f32_e32 v2, v2
	v_pk_mul_f32 v[52:53], v[52:53], v[62:63]
	v_add_f32_e32 v2, 1.0, v2
	v_rcp_f32_e32 v64, v2
	v_mul_f32_e32 v2, 0xbfb8aa3b, v54
	v_exp_f32_e32 v2, v2
	s_nop 0
	v_add_f32_e32 v2, 1.0, v2
	v_rcp_f32_e32 v66, v2
	v_mul_f32_e32 v2, 0xbfb8aa3b, v59
	v_exp_f32_e32 v2, v2
	s_nop 0
	v_add_f32_e32 v2, 1.0, v2
	v_rcp_f32_e32 v65, v2
	v_mul_f32_e32 v2, 0xbfb8aa3b, v55
	v_exp_f32_e32 v2, v2
	v_pk_mul_f32 v[58:59], v[58:59], v[64:65]
	v_add_f32_e32 v2, 1.0, v2
	v_rcp_f32_e32 v67, v2
	s_nop 0
	v_pk_mul_f32 v[54:55], v[54:55], v[66:67]
.LBB0_1249:
	s_mov_b64 s[0:1], 0x100000
	v_lshl_add_u64 v[60:61], v[68:69], 0, s[0:1]
	s_and_b64 vcc, exec, s[42:43]
	v_cvt_pk_bf16_f32 v56, v56, v57
	v_cvt_pk_bf16_f32 v57, v58, v59
	v_cvt_pk_bf16_f32 v58, v52, v53
	v_cvt_pk_bf16_f32 v59, v54, v55
	global_store_dwordx4 v[60:61], v[56:59], off offset:256 sc1
	s_cbranch_vccnz .LBB0_1251
	v_mul_f32_e32 v2, 0xbfb8aa3b, v48
	v_exp_f32_e32 v2, v2
	s_nop 0
	v_add_f32_e32 v2, 1.0, v2
	v_rcp_f32_e32 v52, v2
	v_mul_f32_e32 v2, 0xbfb8aa3b, v44
	v_exp_f32_e32 v2, v2
	s_nop 0
	v_add_f32_e32 v2, 1.0, v2
	v_rcp_f32_e32 v54, v2
	v_mul_f32_e32 v2, 0xbfb8aa3b, v49
	v_exp_f32_e32 v2, v2
	s_nop 0
	v_add_f32_e32 v2, 1.0, v2
	v_rcp_f32_e32 v53, v2
	v_mul_f32_e32 v2, 0xbfb8aa3b, v45
	v_exp_f32_e32 v2, v2
	v_pk_mul_f32 v[48:49], v[48:49], v[52:53]
	v_add_f32_e32 v2, 1.0, v2
	v_rcp_f32_e32 v55, v2
	v_mul_f32_e32 v2, 0xbfb8aa3b, v50
	v_exp_f32_e32 v2, v2
	v_pk_mul_f32 v[44:45], v[44:45], v[54:55]
	v_add_f32_e32 v2, 1.0, v2
	v_rcp_f32_e32 v56, v2
	v_mul_f32_e32 v2, 0xbfb8aa3b, v46
	v_exp_f32_e32 v2, v2
	s_nop 0
	v_add_f32_e32 v2, 1.0, v2
	v_rcp_f32_e32 v58, v2
	v_mul_f32_e32 v2, 0xbfb8aa3b, v51
	v_exp_f32_e32 v2, v2
	s_nop 0
	v_add_f32_e32 v2, 1.0, v2
	v_rcp_f32_e32 v57, v2
	v_mul_f32_e32 v2, 0xbfb8aa3b, v47
	v_exp_f32_e32 v2, v2
	v_pk_mul_f32 v[50:51], v[50:51], v[56:57]
	v_add_f32_e32 v2, 1.0, v2
	v_rcp_f32_e32 v59, v2
	s_nop 0
	v_pk_mul_f32 v[46:47], v[46:47], v[58:59]
.LBB0_1251:
	v_lshlrev_b64 v[52:53], 13, v[144:145]
	v_lshl_add_u64 v[52:53], v[146:147], 0, v[52:53]
	v_cvt_pk_bf16_f32 v48, v48, v49
	v_cvt_pk_bf16_f32 v49, v50, v51
	v_cvt_pk_bf16_f32 v50, v44, v45
	v_add_co_u32_e32 v44, vcc, 0x120000, v52
	v_cvt_pk_bf16_f32 v51, v46, v47
	s_nop 1
	v_addc_co_u32_e32 v45, vcc, 0, v53, vcc
	s_and_b64 vcc, exec, s[42:43]
	global_store_dwordx4 v[44:45], v[48:51], off sc1
	s_cbranch_vccnz .LBB0_1253
	v_mul_f32_e32 v2, 0xbfb8aa3b, v40
	v_exp_f32_e32 v2, v2
	s_nop 0
	v_add_f32_e32 v2, 1.0, v2
	v_rcp_f32_e32 v44, v2
	v_mul_f32_e32 v2, 0xbfb8aa3b, v36
	v_exp_f32_e32 v2, v2
	s_nop 0
	v_add_f32_e32 v2, 1.0, v2
	v_rcp_f32_e32 v46, v2
	v_mul_f32_e32 v2, 0xbfb8aa3b, v41
	v_exp_f32_e32 v2, v2
	s_nop 0
	v_add_f32_e32 v2, 1.0, v2
	v_rcp_f32_e32 v45, v2
	v_mul_f32_e32 v2, 0xbfb8aa3b, v37
	v_exp_f32_e32 v2, v2
	v_pk_mul_f32 v[40:41], v[40:41], v[44:45]
	v_add_f32_e32 v2, 1.0, v2
	v_rcp_f32_e32 v47, v2
	v_mul_f32_e32 v2, 0xbfb8aa3b, v42
	v_exp_f32_e32 v2, v2
	v_pk_mul_f32 v[36:37], v[36:37], v[46:47]
	v_add_f32_e32 v2, 1.0, v2
	v_rcp_f32_e32 v48, v2
	v_mul_f32_e32 v2, 0xbfb8aa3b, v38
	v_exp_f32_e32 v2, v2
	s_nop 0
	v_add_f32_e32 v2, 1.0, v2
	v_rcp_f32_e32 v50, v2
	v_mul_f32_e32 v2, 0xbfb8aa3b, v43
	v_exp_f32_e32 v2, v2
	s_nop 0
	v_add_f32_e32 v2, 1.0, v2
	v_rcp_f32_e32 v49, v2
	v_mul_f32_e32 v2, 0xbfb8aa3b, v39
	v_exp_f32_e32 v2, v2
	v_pk_mul_f32 v[42:43], v[42:43], v[48:49]
	v_add_f32_e32 v2, 1.0, v2
	v_rcp_f32_e32 v51, v2
	s_nop 0
	v_pk_mul_f32 v[38:39], v[38:39], v[50:51]
.LBB0_1253:
	s_mov_b64 s[0:1], 0x120000
	v_lshl_add_u64 v[44:45], v[52:53], 0, s[0:1]
	s_and_b64 vcc, exec, s[42:43]
	v_cvt_pk_bf16_f32 v40, v40, v41
	v_cvt_pk_bf16_f32 v41, v42, v43
	v_cvt_pk_bf16_f32 v42, v36, v37
	v_cvt_pk_bf16_f32 v43, v38, v39
	global_store_dwordx4 v[44:45], v[40:43], off offset:256 sc1
	s_cbranch_vccnz .LBB0_1255
	v_mul_f32_e32 v2, 0xbfb8aa3b, v32
	v_exp_f32_e32 v2, v2
	s_nop 0
	v_add_f32_e32 v2, 1.0, v2
	v_rcp_f32_e32 v36, v2
	v_mul_f32_e32 v2, 0xbfb8aa3b, v28
	v_exp_f32_e32 v2, v2
	s_nop 0
	v_add_f32_e32 v2, 1.0, v2
	v_rcp_f32_e32 v38, v2
	v_mul_f32_e32 v2, 0xbfb8aa3b, v33
	v_exp_f32_e32 v2, v2
	s_nop 0
	v_add_f32_e32 v2, 1.0, v2
	v_rcp_f32_e32 v37, v2
	v_mul_f32_e32 v2, 0xbfb8aa3b, v29
	v_exp_f32_e32 v2, v2
	v_pk_mul_f32 v[32:33], v[32:33], v[36:37]
	v_add_f32_e32 v2, 1.0, v2
	v_rcp_f32_e32 v39, v2
	v_mul_f32_e32 v2, 0xbfb8aa3b, v34
	v_exp_f32_e32 v2, v2
	v_pk_mul_f32 v[28:29], v[28:29], v[38:39]
	v_add_f32_e32 v2, 1.0, v2
	v_rcp_f32_e32 v40, v2
	v_mul_f32_e32 v2, 0xbfb8aa3b, v30
	v_exp_f32_e32 v2, v2
	s_nop 0
	v_add_f32_e32 v2, 1.0, v2
	v_rcp_f32_e32 v42, v2
	v_mul_f32_e32 v2, 0xbfb8aa3b, v35
	v_exp_f32_e32 v2, v2
	s_nop 0
	v_add_f32_e32 v2, 1.0, v2
	v_rcp_f32_e32 v41, v2
	v_mul_f32_e32 v2, 0xbfb8aa3b, v31
	v_exp_f32_e32 v2, v2
	v_pk_mul_f32 v[34:35], v[34:35], v[40:41]
	v_add_f32_e32 v2, 1.0, v2
	v_rcp_f32_e32 v43, v2
	s_nop 0
	v_pk_mul_f32 v[30:31], v[30:31], v[42:43]
.LBB0_1255:
	v_lshlrev_b64 v[36:37], 13, v[144:145]
	v_lshl_add_u64 v[36:37], v[146:147], 0, v[36:37]
	v_cvt_pk_bf16_f32 v32, v32, v33
	v_cvt_pk_bf16_f32 v33, v34, v35
	v_cvt_pk_bf16_f32 v34, v28, v29
	v_add_co_u32_e32 v28, vcc, 0x140000, v36
	v_cvt_pk_bf16_f32 v35, v30, v31
	s_nop 1
	v_addc_co_u32_e32 v29, vcc, 0, v37, vcc
	s_and_b64 vcc, exec, s[42:43]
	global_store_dwordx4 v[28:29], v[32:35], off sc1
	s_cbranch_vccnz .LBB0_1257
	v_mul_f32_e32 v2, 0xbfb8aa3b, v24
	v_exp_f32_e32 v2, v2
	s_nop 0
	v_add_f32_e32 v2, 1.0, v2
	v_rcp_f32_e32 v28, v2
	v_mul_f32_e32 v2, 0xbfb8aa3b, v20
	v_exp_f32_e32 v2, v2
	s_nop 0
	v_add_f32_e32 v2, 1.0, v2
	v_rcp_f32_e32 v30, v2
	v_mul_f32_e32 v2, 0xbfb8aa3b, v25
	v_exp_f32_e32 v2, v2
	s_nop 0
	v_add_f32_e32 v2, 1.0, v2
	v_rcp_f32_e32 v29, v2
	v_mul_f32_e32 v2, 0xbfb8aa3b, v21
	v_exp_f32_e32 v2, v2
	v_pk_mul_f32 v[24:25], v[24:25], v[28:29]
	v_add_f32_e32 v2, 1.0, v2
	v_rcp_f32_e32 v31, v2
	v_mul_f32_e32 v2, 0xbfb8aa3b, v26
	v_exp_f32_e32 v2, v2
	v_pk_mul_f32 v[20:21], v[20:21], v[30:31]
	v_add_f32_e32 v2, 1.0, v2
	v_rcp_f32_e32 v32, v2
	v_mul_f32_e32 v2, 0xbfb8aa3b, v22
	v_exp_f32_e32 v2, v2
	s_nop 0
	v_add_f32_e32 v2, 1.0, v2
	v_rcp_f32_e32 v34, v2
	v_mul_f32_e32 v2, 0xbfb8aa3b, v27
	v_exp_f32_e32 v2, v2
	s_nop 0
	v_add_f32_e32 v2, 1.0, v2
	v_rcp_f32_e32 v33, v2
	v_mul_f32_e32 v2, 0xbfb8aa3b, v23
	v_exp_f32_e32 v2, v2
	v_pk_mul_f32 v[26:27], v[26:27], v[32:33]
	v_add_f32_e32 v2, 1.0, v2
	v_rcp_f32_e32 v35, v2
	s_nop 0
	v_pk_mul_f32 v[22:23], v[22:23], v[34:35]
.LBB0_1257:
	s_mov_b64 s[0:1], 0x140000
	v_lshl_add_u64 v[28:29], v[36:37], 0, s[0:1]
	s_and_b64 vcc, exec, s[42:43]
	v_cvt_pk_bf16_f32 v24, v24, v25
	v_cvt_pk_bf16_f32 v25, v26, v27
	v_cvt_pk_bf16_f32 v26, v20, v21
	v_cvt_pk_bf16_f32 v27, v22, v23
	global_store_dwordx4 v[28:29], v[24:27], off offset:256 sc1
	s_cbranch_vccnz .LBB0_1259
	v_mul_f32_e32 v2, 0xbfb8aa3b, v16
	v_exp_f32_e32 v2, v2
	s_nop 0
	v_add_f32_e32 v2, 1.0, v2
	v_rcp_f32_e32 v20, v2
	v_mul_f32_e32 v2, 0xbfb8aa3b, v12
	v_exp_f32_e32 v2, v2
	s_nop 0
	v_add_f32_e32 v2, 1.0, v2
	v_rcp_f32_e32 v22, v2
	v_mul_f32_e32 v2, 0xbfb8aa3b, v17
	v_exp_f32_e32 v2, v2
	s_nop 0
	v_add_f32_e32 v2, 1.0, v2
	v_rcp_f32_e32 v21, v2
	v_mul_f32_e32 v2, 0xbfb8aa3b, v13
	v_exp_f32_e32 v2, v2
	v_pk_mul_f32 v[16:17], v[16:17], v[20:21]
	v_add_f32_e32 v2, 1.0, v2
	v_rcp_f32_e32 v23, v2
	v_mul_f32_e32 v2, 0xbfb8aa3b, v18
	v_exp_f32_e32 v2, v2
	v_pk_mul_f32 v[12:13], v[12:13], v[22:23]
	v_add_f32_e32 v2, 1.0, v2
	v_rcp_f32_e32 v24, v2
	v_mul_f32_e32 v2, 0xbfb8aa3b, v14
	v_exp_f32_e32 v2, v2
	s_nop 0
	v_add_f32_e32 v2, 1.0, v2
	v_rcp_f32_e32 v26, v2
	v_mul_f32_e32 v2, 0xbfb8aa3b, v19
	v_exp_f32_e32 v2, v2
	s_nop 0
	v_add_f32_e32 v2, 1.0, v2
	v_rcp_f32_e32 v25, v2
	v_mul_f32_e32 v2, 0xbfb8aa3b, v15
	v_exp_f32_e32 v2, v2
	v_pk_mul_f32 v[18:19], v[18:19], v[24:25]
	v_add_f32_e32 v2, 1.0, v2
	v_rcp_f32_e32 v27, v2
	s_nop 0
	v_pk_mul_f32 v[14:15], v[14:15], v[26:27]
.LBB0_1259:
	v_lshlrev_b64 v[20:21], 13, v[144:145]
	v_lshl_add_u64 v[20:21], v[146:147], 0, v[20:21]
	v_cvt_pk_bf16_f32 v16, v16, v17
	v_cvt_pk_bf16_f32 v17, v18, v19
	v_cvt_pk_bf16_f32 v18, v12, v13
	v_add_co_u32_e32 v12, vcc, 0x160000, v20
	v_cvt_pk_bf16_f32 v19, v14, v15
	s_nop 1
	v_addc_co_u32_e32 v13, vcc, 0, v21, vcc
	s_and_b64 vcc, exec, s[42:43]
	global_store_dwordx4 v[12:13], v[16:19], off sc1
	s_cbranch_vccnz .LBB0_1261
	v_mul_f32_e32 v2, 0xbfb8aa3b, v8
	v_exp_f32_e32 v2, v2
	s_nop 0
	v_add_f32_e32 v2, 1.0, v2
	v_rcp_f32_e32 v12, v2
	v_mul_f32_e32 v2, 0xbfb8aa3b, v4
	v_exp_f32_e32 v2, v2
	s_nop 0
	v_add_f32_e32 v2, 1.0, v2
	v_rcp_f32_e32 v14, v2
	v_mul_f32_e32 v2, 0xbfb8aa3b, v9
	v_exp_f32_e32 v2, v2
	s_nop 0
	v_add_f32_e32 v2, 1.0, v2
	v_rcp_f32_e32 v13, v2
	v_mul_f32_e32 v2, 0xbfb8aa3b, v5
	v_exp_f32_e32 v2, v2
	v_pk_mul_f32 v[8:9], v[8:9], v[12:13]
	v_add_f32_e32 v2, 1.0, v2
	v_rcp_f32_e32 v15, v2
	v_mul_f32_e32 v2, 0xbfb8aa3b, v10
	v_exp_f32_e32 v2, v2
	v_pk_mul_f32 v[4:5], v[4:5], v[14:15]
	v_add_f32_e32 v2, 1.0, v2
	v_rcp_f32_e32 v16, v2
	v_mul_f32_e32 v2, 0xbfb8aa3b, v6
	v_exp_f32_e32 v2, v2
	s_nop 0
	v_add_f32_e32 v2, 1.0, v2
	v_rcp_f32_e32 v18, v2
	v_mul_f32_e32 v2, 0xbfb8aa3b, v11
	v_exp_f32_e32 v2, v2
	s_nop 0
	v_add_f32_e32 v2, 1.0, v2
	v_rcp_f32_e32 v17, v2
	v_mul_f32_e32 v2, 0xbfb8aa3b, v7
	v_exp_f32_e32 v2, v2
	v_pk_mul_f32 v[10:11], v[10:11], v[16:17]
	v_add_f32_e32 v2, 1.0, v2
	v_rcp_f32_e32 v19, v2
	s_nop 0
	v_pk_mul_f32 v[6:7], v[6:7], v[18:19]
.LBB0_1261:
	s_mov_b64 s[0:1], 0x160000
	v_lshl_add_u64 v[12:13], v[20:21], 0, s[0:1]
	s_and_b64 vcc, exec, s[40:41]
	s_mov_b64 s[0:1], -1
	v_cvt_pk_bf16_f32 v8, v8, v9
	v_cvt_pk_bf16_f32 v9, v10, v11
	v_cvt_pk_bf16_f32 v10, v4, v5
	v_cvt_pk_bf16_f32 v11, v6, v7
	global_store_dwordx4 v[12:13], v[8:11], off offset:256 sc1
	s_cbranch_vccnz .LBB0_1214
	s_andn2_b64 vcc, exec, s[4:5]
	s_cbranch_vccnz .LBB0_1213
	s_barrier
	s_branch .LBB0_1213
